# S5 prompt scan F*Hin row kk=1: two alternating table buffers with counted vmcnt(1) instead of load-wait-MFMA per step
# baseline (speedup 1.0000x reference)
.LBB0_814:
	v_lshl_add_u64 v[238:239], s[40:41], 0, v[2:3]
	v_add_co_u32_e32 v132, vcc, 0x28000, v238
	v_lshl_add_u64 v[196:197], s[34:35], 1, v[186:187]
	s_nop 0
	v_addc_co_u32_e32 v133, vcc, 0, v239, vcc
	global_load_dwordx4 v[136:139], v[132:133], off offset:1024
	v_add_co_u32_e32 v132, vcc, 0x2a000, v238
	v_lshl_add_u64 v[202:203], v[238:239], 0, s[58:59]
	s_nop 0
	v_addc_co_u32_e32 v133, vcc, 0, v239, vcc
	global_load_dwordx4 v[140:143], v[132:133], off offset:1024
	v_add_co_u32_e32 v134, vcc, 0x2c000, v238
	s_mov_b32 s3, 0
	s_nop 0
	v_addc_co_u32_e32 v135, vcc, 0, v239, vcc
	global_load_dwordx4 v[230:233], v[134:135], off offset:1024
	s_waitcnt vmcnt(2)
	v_mfma_f32_32x32x16_bf16 v[116:131], v[136:139], v[174:177], v[116:131]
	v_add_co_u32_e32 v136, vcc, 0x2e000, v238
	s_nop 1
	v_addc_co_u32_e32 v137, vcc, 0, v239, vcc
	v_add_co_u32_e32 v138, vcc, 0x30000, v238
	s_waitcnt vmcnt(1)
	v_mfma_f32_32x32x16_bf16 v[100:115], v[140:143], v[174:177], v[100:115]
	global_load_dwordx4 v[142:145], v[136:137], off offset:1024
	v_addc_co_u32_e32 v139, vcc, 0, v239, vcc
	v_add_co_u32_e32 v140, vcc, 0x32000, v238
	s_nop 1
	v_addc_co_u32_e32 v141, vcc, 0, v239, vcc
	s_waitcnt vmcnt(1)
	v_mfma_f32_32x32x16_bf16 v[84:99], v[230:233], v[174:177], v[84:99]
	global_load_dwordx4 v[230:233], v[138:139], off offset:1024
	global_load_dwordx4 v[234:237], v[140:141], off offset:1024
	s_waitcnt vmcnt(2)
	v_mfma_f32_32x32x16_bf16 v[68:83], v[142:145], v[174:177], v[68:83]
	v_add_co_u32_e32 v142, vcc, 0x34000, v238
	s_nop 1
	v_addc_co_u32_e32 v143, vcc, 0, v239, vcc
	v_add_co_u32_e32 v144, vcc, 0x36000, v238
	s_waitcnt vmcnt(1)
	v_mfma_f32_32x32x16_bf16 v[52:67], v[230:233], v[174:177], v[52:67]
	v_addc_co_u32_e32 v145, vcc, 0, v239, vcc
	global_load_dwordx4 v[230:233], v[142:143], off offset:1024
	s_waitcnt vmcnt(1)
	v_mfma_f32_32x32x16_bf16 v[36:51], v[234:237], v[174:177], v[36:51]
	global_load_dwordx4 v[234:237], v[144:145], off offset:1024
	s_waitcnt vmcnt(1)
	v_mfma_f32_32x32x16_bf16 v[20:35], v[230:233], v[174:177], v[20:35]
	s_waitcnt vmcnt(0)
	v_mfma_f32_32x32x16_bf16 v[4:19], v[234:237], v[174:177], v[4:19]
	global_load_dwordx4 v[230:233], v[202:203], off offset:1024
	global_load_dwordx4 v[234:237], v[132:133], off offset:2048
	s_waitcnt vmcnt(1)
	v_mfma_f32_32x32x16_bf16 v[116:131], v[230:233], v[170:173], v[116:131]
	global_load_dwordx4 v[230:233], v[134:135], off offset:2048
	s_waitcnt vmcnt(1)
	v_mfma_f32_32x32x16_bf16 v[100:115], v[234:237], v[170:173], v[100:115]
	global_load_dwordx4 v[234:237], v[136:137], off offset:2048
	s_waitcnt vmcnt(1)
	v_mfma_f32_32x32x16_bf16 v[84:99], v[230:233], v[170:173], v[84:99]
	global_load_dwordx4 v[230:233], v[138:139], off offset:2048
	s_waitcnt vmcnt(1)
	v_mfma_f32_32x32x16_bf16 v[68:83], v[234:237], v[170:173], v[68:83]
	global_load_dwordx4 v[234:237], v[140:141], off offset:2048
	s_waitcnt vmcnt(1)
	v_mfma_f32_32x32x16_bf16 v[52:67], v[230:233], v[170:173], v[52:67]
	global_load_dwordx4 v[230:233], v[142:143], off offset:2048
	s_waitcnt vmcnt(1)
	v_mfma_f32_32x32x16_bf16 v[36:51], v[234:237], v[170:173], v[36:51]
	global_load_dwordx4 v[234:237], v[144:145], off offset:2048
	s_waitcnt vmcnt(1)
	v_mfma_f32_32x32x16_bf16 v[20:35], v[230:233], v[170:173], v[20:35]
	s_waitcnt vmcnt(0)
	v_mfma_f32_32x32x16_bf16 v[4:19], v[234:237], v[170:173], v[4:19]
	global_load_dwordx4 v[230:233], v[202:203], off offset:2048
	global_load_dwordx4 v[234:237], v[132:133], off offset:3072
	s_waitcnt vmcnt(1)
	v_mfma_f32_32x32x16_bf16 v[116:131], v[230:233], v[166:169], v[116:131]
	global_load_dwordx4 v[230:233], v[134:135], off offset:3072
	s_waitcnt vmcnt(1)
	v_mfma_f32_32x32x16_bf16 v[100:115], v[234:237], v[166:169], v[100:115]
	global_load_dwordx4 v[234:237], v[136:137], off offset:3072
	s_waitcnt vmcnt(1)
	v_mfma_f32_32x32x16_bf16 v[84:99], v[230:233], v[166:169], v[84:99]
	global_load_dwordx4 v[230:233], v[138:139], off offset:3072
	s_waitcnt vmcnt(1)
	v_mfma_f32_32x32x16_bf16 v[68:83], v[234:237], v[166:169], v[68:83]
	global_load_dwordx4 v[234:237], v[140:141], off offset:3072
	s_waitcnt vmcnt(1)
	v_mfma_f32_32x32x16_bf16 v[52:67], v[230:233], v[166:169], v[52:67]
	global_load_dwordx4 v[230:233], v[142:143], off offset:3072
	s_waitcnt vmcnt(1)
	v_mfma_f32_32x32x16_bf16 v[36:51], v[234:237], v[166:169], v[36:51]
	global_load_dwordx4 v[234:237], v[144:145], off offset:3072
	s_waitcnt vmcnt(1)
	v_mfma_f32_32x32x16_bf16 v[20:35], v[230:233], v[166:169], v[20:35]
	s_waitcnt vmcnt(0)
	v_mfma_f32_32x32x16_bf16 v[4:19], v[234:237], v[166:169], v[4:19]
	v_add_co_u32_e32 v240, vcc, s71, v238
	global_load_dwordx4 v[230:233], v[202:203], off offset:3072
	s_nop 0
	v_addc_co_u32_e32 v241, vcc, 0, v239, vcc
	global_load_dwordx4 v[234:237], v[240:241], off
	v_add_co_u32_e32 v242, vcc, s72, v238
	s_waitcnt vmcnt(1)
	v_mfma_f32_32x32x16_bf16 v[116:131], v[230:233], v[162:165], v[116:131]
	v_addc_co_u32_e32 v243, vcc, 0, v239, vcc
	v_add_co_u32_e32 v244, vcc, s73, v238
	global_load_dwordx4 v[230:233], v[242:243], off
	s_nop 0
	v_addc_co_u32_e32 v245, vcc, 0, v239, vcc
	s_waitcnt vmcnt(1)
	v_mfma_f32_32x32x16_bf16 v[100:115], v[234:237], v[162:165], v[100:115]
	global_load_dwordx4 v[234:237], v[244:245], off
	v_add_co_u32_e32 v246, vcc, s74, v238
	s_nop 1
	v_addc_co_u32_e32 v247, vcc, 0, v239, vcc
	v_add_co_u32_e32 v248, vcc, s75, v238
	s_waitcnt vmcnt(1)
	v_mfma_f32_32x32x16_bf16 v[84:99], v[230:233], v[162:165], v[84:99]
	v_addc_co_u32_e32 v249, vcc, 0, v239, vcc
	global_load_dwordx4 v[230:233], v[246:247], off
	v_add_co_u32_e32 v250, vcc, s76, v238
	s_nop 1
	v_addc_co_u32_e32 v251, vcc, 0, v239, vcc
	s_waitcnt vmcnt(1)
	v_mfma_f32_32x32x16_bf16 v[68:83], v[234:237], v[162:165], v[68:83]
	global_load_dwordx4 v[234:237], v[248:249], off
	v_add_co_u32_e32 v252, vcc, s79, v238
	s_nop 1
	v_addc_co_u32_e32 v253, vcc, 0, v239, vcc
	v_add_co_u32_e32 v206, vcc, s77, v238
	s_waitcnt vmcnt(1)
	v_mfma_f32_32x32x16_bf16 v[52:67], v[230:233], v[162:165], v[52:67]
	global_load_dwordx4 v[230:233], v[250:251], off
	v_addc_co_u32_e32 v207, vcc, 0, v239, vcc
	s_waitcnt vmcnt(1)
	v_mfma_f32_32x32x16_bf16 v[36:51], v[234:237], v[162:165], v[36:51]
	global_load_dwordx4 v[234:237], v[252:253], off offset:-4096
	s_waitcnt vmcnt(1)
	v_mfma_f32_32x32x16_bf16 v[20:35], v[230:233], v[162:165], v[20:35]
	s_waitcnt vmcnt(0)
	v_mfma_f32_32x32x16_bf16 v[4:19], v[234:237], v[162:165], v[4:19]
	global_load_dwordx4 v[230:233], v[240:241], off offset:1024
	global_load_dwordx4 v[234:237], v[242:243], off offset:1024
	v_add_co_u32_e32 v238, vcc, s78, v238
	s_waitcnt vmcnt(1)
	v_mfma_f32_32x32x16_bf16 v[100:115], v[230:233], v[158:161], v[100:115]
	global_load_dwordx4 v[230:233], v[244:245], off offset:1024
	v_addc_co_u32_e32 v239, vcc, 0, v239, vcc
	s_waitcnt vmcnt(1)
	v_mfma_f32_32x32x16_bf16 v[84:99], v[234:237], v[158:161], v[84:99]
	global_load_dwordx4 v[234:237], v[246:247], off offset:1024
	s_waitcnt vmcnt(1)
	v_mfma_f32_32x32x16_bf16 v[68:83], v[230:233], v[158:161], v[68:83]
	global_load_dwordx4 v[230:233], v[248:249], off offset:1024
	s_waitcnt vmcnt(1)
	v_mfma_f32_32x32x16_bf16 v[52:67], v[234:237], v[158:161], v[52:67]
	global_load_dwordx4 v[234:237], v[250:251], off offset:1024
	s_waitcnt vmcnt(1)
	v_mfma_f32_32x32x16_bf16 v[36:51], v[230:233], v[158:161], v[36:51]
	global_load_dwordx4 v[230:233], v[238:239], off offset:1024
	s_waitcnt vmcnt(1)
	v_mfma_f32_32x32x16_bf16 v[20:35], v[234:237], v[158:161], v[20:35]
	global_load_dwordx4 v[234:237], v[206:207], off offset:1024
	s_waitcnt vmcnt(1)
	v_mfma_f32_32x32x16_bf16 v[116:131], v[230:233], v[158:161], v[116:131]
	s_waitcnt vmcnt(0)
	v_mfma_f32_32x32x16_bf16 v[4:19], v[234:237], v[158:161], v[4:19]
	global_load_dwordx4 v[230:233], v[238:239], off offset:2048
	global_load_dwordx4 v[234:237], v[240:241], off offset:2048
	s_waitcnt vmcnt(1)
	v_mfma_f32_32x32x16_bf16 v[116:131], v[230:233], v[154:157], v[116:131]
	global_load_dwordx4 v[230:233], v[242:243], off offset:2048
	s_waitcnt vmcnt(1)
	v_mfma_f32_32x32x16_bf16 v[100:115], v[234:237], v[154:157], v[100:115]
	global_load_dwordx4 v[234:237], v[244:245], off offset:2048
	s_waitcnt vmcnt(1)
	v_mfma_f32_32x32x16_bf16 v[84:99], v[230:233], v[154:157], v[84:99]
	global_load_dwordx4 v[230:233], v[246:247], off offset:2048
	s_waitcnt vmcnt(1)
	v_mfma_f32_32x32x16_bf16 v[68:83], v[234:237], v[154:157], v[68:83]
	global_load_dwordx4 v[234:237], v[248:249], off offset:2048
	s_waitcnt vmcnt(1)
	v_mfma_f32_32x32x16_bf16 v[52:67], v[230:233], v[154:157], v[52:67]
	global_load_dwordx4 v[230:233], v[250:251], off offset:2048
	s_waitcnt vmcnt(1)
	v_mfma_f32_32x32x16_bf16 v[36:51], v[234:237], v[154:157], v[36:51]
	global_load_dwordx4 v[234:237], v[206:207], off offset:2048
	s_waitcnt vmcnt(1)
	v_mfma_f32_32x32x16_bf16 v[20:35], v[230:233], v[154:157], v[20:35]
	s_waitcnt vmcnt(0)
	v_mfma_f32_32x32x16_bf16 v[4:19], v[234:237], v[154:157], v[4:19]
	global_load_dwordx4 v[230:233], v[238:239], off offset:3072
	global_load_dwordx4 v[234:237], v[240:241], off offset:3072
	s_nop 0
	global_load_dwordx4 v[238:241], v[206:207], off offset:3072
	s_waitcnt vmcnt(2)
	v_mfma_f32_32x32x16_bf16 v[116:131], v[230:233], v[150:153], v[116:131]
	global_load_dwordx4 v[230:233], v[242:243], off offset:3072
	s_waitcnt vmcnt(2)
	v_mfma_f32_32x32x16_bf16 v[100:115], v[234:237], v[150:153], v[100:115]
	global_load_dwordx4 v[234:237], v[244:245], off offset:3072
	s_waitcnt vmcnt(2)
	v_mfma_f32_32x32x16_bf16 v[4:19], v[238:241], v[150:153], v[4:19]
	s_waitcnt vmcnt(1)
	v_mfma_f32_32x32x16_bf16 v[84:99], v[230:233], v[150:153], v[84:99]
	global_load_dwordx4 v[230:233], v[246:247], off offset:3072
	s_waitcnt vmcnt(1)
	v_mfma_f32_32x32x16_bf16 v[68:83], v[234:237], v[150:153], v[68:83]
	global_load_dwordx4 v[234:237], v[248:249], off offset:3072
	s_waitcnt vmcnt(1)
	v_mfma_f32_32x32x16_bf16 v[52:67], v[230:233], v[150:153], v[52:67]
	global_load_dwordx4 v[230:233], v[250:251], off offset:3072
	s_waitcnt vmcnt(1)
	v_mfma_f32_32x32x16_bf16 v[36:51], v[234:237], v[150:153], v[36:51]
	s_waitcnt vmcnt(0)
	v_mfma_f32_32x32x16_bf16 v[20:35], v[230:233], v[150:153], v[20:35]
	global_load_dwordx4 v[230:233], v[132:133], off
	s_nop 0
	global_load_dwordx4 v[132:135], v[134:135], off
	s_waitcnt vmcnt(1)
	v_mfma_f32_32x32x16_bf16 v[116:131], v[230:233], v[146:149], v[116:131]
	global_load_dwordx4 v[230:233], v[136:137], off
	s_waitcnt vmcnt(1)
	v_mfma_f32_32x32x16_bf16 v[100:115], v[132:135], v[146:149], v[100:115]
	global_load_dwordx4 v[132:135], v[138:139], off
	s_nop 0
	global_load_dwordx4 v[136:139], v[140:141], off
	s_waitcnt vmcnt(2)
	v_mfma_f32_32x32x16_bf16 v[84:99], v[230:233], v[146:149], v[84:99]
	s_waitcnt vmcnt(1)
	v_mfma_f32_32x32x16_bf16 v[68:83], v[132:135], v[146:149], v[68:83]
	global_load_dwordx4 v[132:135], v[142:143], off
	s_waitcnt vmcnt(1)
	v_mfma_f32_32x32x16_bf16 v[52:67], v[136:139], v[146:149], v[52:67]
	global_load_dwordx4 v[136:139], v[144:145], off
	s_waitcnt vmcnt(1)
	v_mfma_f32_32x32x16_bf16 v[36:51], v[132:135], v[146:149], v[36:51]
	global_load_dwordx4 v[132:135], v[252:253], off
	s_waitcnt vmcnt(1)
	v_mfma_f32_32x32x16_bf16 v[20:35], v[136:139], v[146:149], v[20:35]
	s_waitcnt vmcnt(0)
	v_mfma_f32_32x32x16_bf16 v[4:19], v[132:135], v[146:149], v[4:19]
	v_mul_f32_e32 v2, 0x3d372713, v116
	v_mul_f32_e32 v2, v116, v2
	v_mul_f32_e32 v133, 0x3d372713, v117
	v_fma_f32 v2, v116, v2, v116
	v_mul_f32_e32 v133, v117, v133
	v_mul_f32_e32 v2, 0x3f4c422a, v2
	v_fma_f32 v133, v117, v133, v117
	v_add_f32_e32 v2, v2, v2
	v_mul_f32_e32 v133, 0x3f4c422a, v133
	v_mul_f32_e32 v2, 0x3fb8aa3b, v2
	v_add_f32_e32 v133, v133, v133
	v_exp_f32_e32 v2, v2
	v_mul_f32_e32 v133, 0x3fb8aa3b, v133
	v_exp_f32_e32 v133, v133
	v_mul_f32_e32 v136, 0x3d372713, v119
	v_add_f32_e32 v2, 1.0, v2
	v_rcp_f32_e32 v134, v2
	v_add_f32_e32 v2, 1.0, v133
	v_rcp_f32_e32 v135, v2
	v_mul_f32_e32 v2, 0x3d372713, v118
	v_mul_f32_e32 v2, v118, v2
	v_fma_f32 v2, v118, v2, v118
	v_mul_f32_e32 v136, v119, v136
	v_mul_f32_e32 v2, 0x3f4c422a, v2
	v_fma_f32 v136, v119, v136, v119
	v_add_f32_e32 v2, v2, v2
	v_mul_f32_e32 v136, 0x3f4c422a, v136
	v_mul_f32_e32 v2, 0x3fb8aa3b, v2
	v_add_f32_e32 v136, v136, v136
	v_exp_f32_e32 v2, v2
	v_mul_f32_e32 v136, 0x3fb8aa3b, v136
	v_exp_f32_e32 v137, v136
	v_pk_fma_f32 v[134:135], v[134:135], 2.0, 1.0 op_sel_hi:[1,0,0] neg_lo:[1,0,0] neg_hi:[1,0,0]
	v_add_f32_e32 v2, 1.0, v2
	v_pk_mul_f32 v[116:117], v[116:117], 0.5 op_sel_hi:[1,0]
	v_rcp_f32_e32 v136, v2
	v_add_f32_e32 v2, 1.0, v137
	v_pk_add_f32 v[134:135], v[134:135], 1.0 op_sel_hi:[1,0]
	v_rcp_f32_e32 v137, v2
	v_pk_mul_f32 v[116:117], v[116:117], v[134:135]
	v_mul_f32_e32 v2, 0x3d372713, v120
	v_cvt_pk_bf16_f32 v116, v116, v117
	v_mul_f32_e32 v2, v120, v2
	v_mul_f32_e32 v117, 0x3d372713, v121
	v_fma_f32 v2, v120, v2, v120
	v_mul_f32_e32 v117, v121, v117
	v_mul_f32_e32 v2, 0x3f4c422a, v2
	v_fma_f32 v117, v121, v117, v121
	v_add_f32_e32 v2, v2, v2
	v_mul_f32_e32 v117, 0x3f4c422a, v117
	v_mul_f32_e32 v2, 0x3fb8aa3b, v2
	v_add_f32_e32 v117, v117, v117
	v_exp_f32_e32 v2, v2
	v_mul_f32_e32 v117, 0x3fb8aa3b, v117
	v_exp_f32_e32 v117, v117
	v_pk_fma_f32 v[134:135], v[136:137], 2.0, 1.0 op_sel_hi:[1,0,0] neg_lo:[1,0,0] neg_hi:[1,0,0]
	v_add_f32_e32 v2, 1.0, v2
	v_pk_mul_f32 v[118:119], v[118:119], 0.5 op_sel_hi:[1,0]
	v_pk_add_f32 v[134:135], v[134:135], 1.0 op_sel_hi:[1,0]
	v_rcp_f32_e32 v136, v2
	v_add_f32_e32 v2, 1.0, v117
	v_rcp_f32_e32 v137, v2
	v_pk_mul_f32 v[118:119], v[118:119], v[134:135]
	v_mul_f32_e32 v2, 0x3d372713, v122
	v_cvt_pk_bf16_f32 v117, v118, v119
	v_mul_f32_e32 v2, v122, v2
	v_mul_f32_e32 v118, 0x3d372713, v123
	v_fma_f32 v2, v122, v2, v122
	v_mul_f32_e32 v118, v123, v118
	v_mul_f32_e32 v2, 0x3f4c422a, v2
	v_fma_f32 v118, v123, v118, v123
	v_add_f32_e32 v2, v2, v2
	v_mul_f32_e32 v118, 0x3f4c422a, v118
	v_mul_f32_e32 v2, 0x3fb8aa3b, v2
	v_add_f32_e32 v118, v118, v118
	v_mov_b32_e32 v132, v1
	v_exp_f32_e32 v2, v2
	v_mul_f32_e32 v118, 0x3fb8aa3b, v118
	v_exp_f32_e32 v134, v118
	v_ashrrev_i32_e32 v133, 31, v132
	v_lshlrev_b64 v[132:133], 12, v[132:133]
	v_lshl_add_u64 v[132:133], v[196:197], 0, v[132:133]
	global_store_dwordx2 v[132:133], v[116:117], off
	v_pk_fma_f32 v[116:117], v[136:137], 2.0, 1.0 op_sel_hi:[1,0,0] neg_lo:[1,0,0] neg_hi:[1,0,0]
	v_add_f32_e32 v2, 1.0, v2
	v_pk_mul_f32 v[118:119], v[120:121], 0.5 op_sel_hi:[1,0]
	v_rcp_f32_e32 v120, v2
	v_add_f32_e32 v2, 1.0, v134
	v_pk_add_f32 v[116:117], v[116:117], 1.0 op_sel_hi:[1,0]
	v_rcp_f32_e32 v121, v2
	v_pk_mul_f32 v[116:117], v[118:119], v[116:117]
	v_mul_f32_e32 v2, 0x3d372713, v124
	v_cvt_pk_bf16_f32 v116, v116, v117
	v_mul_f32_e32 v2, v124, v2
	v_mul_f32_e32 v117, 0x3d372713, v125
	v_fma_f32 v2, v124, v2, v124
	v_mul_f32_e32 v117, v125, v117
	v_mul_f32_e32 v2, 0x3f4c422a, v2
	v_fma_f32 v117, v125, v117, v125
	v_add_f32_e32 v2, v2, v2
	v_mul_f32_e32 v117, 0x3f4c422a, v117
	v_mul_f32_e32 v2, 0x3fb8aa3b, v2
	v_add_f32_e32 v117, v117, v117
	v_exp_f32_e32 v2, v2
	v_mul_f32_e32 v117, 0x3fb8aa3b, v117
	v_exp_f32_e32 v117, v117
	v_pk_fma_f32 v[118:119], v[120:121], 2.0, 1.0 op_sel_hi:[1,0,0] neg_lo:[1,0,0] neg_hi:[1,0,0]
	v_add_f32_e32 v2, 1.0, v2
	v_pk_mul_f32 v[120:121], v[122:123], 0.5 op_sel_hi:[1,0]
	v_pk_add_f32 v[118:119], v[118:119], 1.0 op_sel_hi:[1,0]
	v_rcp_f32_e32 v122, v2
	v_add_f32_e32 v2, 1.0, v117
	v_rcp_f32_e32 v123, v2
	v_pk_mul_f32 v[118:119], v[120:121], v[118:119]
	v_mul_f32_e32 v2, 0x3d372713, v126
	v_cvt_pk_bf16_f32 v117, v118, v119
	v_mul_f32_e32 v2, v126, v2
	v_mul_f32_e32 v118, 0x3d372713, v127
	v_fma_f32 v2, v126, v2, v126
	v_mul_f32_e32 v118, v127, v118
	v_mul_f32_e32 v2, 0x3f4c422a, v2
	v_fma_f32 v118, v127, v118, v127
	v_add_f32_e32 v2, v2, v2
	v_mul_f32_e32 v118, 0x3f4c422a, v118
	v_mul_f32_e32 v2, 0x3fb8aa3b, v2
	v_add_f32_e32 v118, v118, v118
	v_exp_f32_e32 v2, v2
	v_mul_f32_e32 v118, 0x3fb8aa3b, v118
	v_exp_f32_e32 v121, v118
	global_store_dwordx2 v[132:133], v[116:117], off offset:16
	v_pk_fma_f32 v[116:117], v[122:123], 2.0, 1.0 op_sel_hi:[1,0,0] neg_lo:[1,0,0] neg_hi:[1,0,0]
	v_add_f32_e32 v2, 1.0, v2
	v_pk_mul_f32 v[118:119], v[124:125], 0.5 op_sel_hi:[1,0]
	v_rcp_f32_e32 v120, v2
	v_add_f32_e32 v2, 1.0, v121
	v_pk_add_f32 v[116:117], v[116:117], 1.0 op_sel_hi:[1,0]
	v_rcp_f32_e32 v121, v2
	v_pk_mul_f32 v[116:117], v[118:119], v[116:117]
	v_mul_f32_e32 v2, 0x3d372713, v128
	v_cvt_pk_bf16_f32 v116, v116, v117
	v_mul_f32_e32 v2, v128, v2
	v_mul_f32_e32 v117, 0x3d372713, v129
	v_fma_f32 v2, v128, v2, v128
	v_mul_f32_e32 v117, v129, v117
	v_mul_f32_e32 v2, 0x3f4c422a, v2
	v_fma_f32 v117, v129, v117, v129
	v_add_f32_e32 v2, v2, v2
	v_mul_f32_e32 v117, 0x3f4c422a, v117
	v_pk_fma_f32 v[118:119], v[120:121], 2.0, 1.0 op_sel_hi:[1,0,0] neg_lo:[1,0,0] neg_hi:[1,0,0]
	v_mul_f32_e32 v2, 0x3fb8aa3b, v2
	v_add_f32_e32 v117, v117, v117
	v_pk_mul_f32 v[120:121], v[126:127], 0.5 op_sel_hi:[1,0]
	v_pk_add_f32 v[118:119], v[118:119], 1.0 op_sel_hi:[1,0]
	v_exp_f32_e32 v2, v2
	v_mul_f32_e32 v117, 0x3fb8aa3b, v117
	v_pk_mul_f32 v[118:119], v[120:121], v[118:119]
	v_exp_f32_e32 v120, v117
	v_add_f32_e32 v2, 1.0, v2
	v_cvt_pk_bf16_f32 v117, v118, v119
	v_rcp_f32_e32 v118, v2
	v_add_f32_e32 v2, 1.0, v120
	v_rcp_f32_e32 v119, v2
	v_add_co_u32_e32 v120, vcc, s70, v132
	v_mul_f32_e32 v2, 0x3d372713, v130
	s_nop 0
	v_addc_co_u32_e32 v121, vcc, 0, v133, vcc
	global_store_dwordx2 v[120:121], v[116:117], off
	v_pk_fma_f32 v[116:117], v[118:119], 2.0, 1.0 op_sel_hi:[1,0,0] neg_lo:[1,0,0] neg_hi:[1,0,0]
	v_mul_f32_e32 v2, v130, v2
	v_mul_f32_e32 v118, 0x3d372713, v131
	v_fma_f32 v2, v130, v2, v130
	v_mul_f32_e32 v118, v131, v118
	v_mul_f32_e32 v2, 0x3f4c422a, v2
	v_fma_f32 v118, v131, v118, v131
	v_add_f32_e32 v2, v2, v2
	v_mul_f32_e32 v118, 0x3f4c422a, v118
	v_mul_f32_e32 v2, 0x3fb8aa3b, v2
	v_add_f32_e32 v118, v118, v118
	v_exp_f32_e32 v2, v2
	v_mul_f32_e32 v118, 0x3fb8aa3b, v118
	v_exp_f32_e32 v123, v118
	v_pk_mul_f32 v[118:119], v[128:129], 0.5 op_sel_hi:[1,0]
	v_add_f32_e32 v2, 1.0, v2
	v_rcp_f32_e32 v122, v2
	v_add_f32_e32 v2, 1.0, v123
	v_rcp_f32_e32 v123, v2
	v_pk_add_f32 v[116:117], v[116:117], 1.0 op_sel_hi:[1,0]
	s_nop 0
	v_pk_mul_f32 v[116:117], v[118:119], v[116:117]
	v_pk_fma_f32 v[118:119], v[122:123], 2.0, 1.0 op_sel_hi:[1,0,0] neg_lo:[1,0,0] neg_hi:[1,0,0]
	v_pk_mul_f32 v[122:123], v[130:131], 0.5 op_sel_hi:[1,0]
	v_pk_add_f32 v[118:119], v[118:119], 1.0 op_sel_hi:[1,0]
	v_cvt_pk_bf16_f32 v116, v116, v117
	v_pk_mul_f32 v[118:119], v[122:123], v[118:119]
	s_nop 0
	v_cvt_pk_bf16_f32 v117, v118, v119
	global_store_dwordx2 v[120:121], v[116:117], off offset:16
	v_mul_f32_e32 v2, 0x3d372713, v100
	v_mul_f32_e32 v2, v100, v2
	v_mul_f32_e32 v117, 0x3d372713, v101
	v_fma_f32 v2, v100, v2, v100
	v_mul_f32_e32 v117, v101, v117
	v_mul_f32_e32 v2, 0x3f4c422a, v2
	v_fma_f32 v117, v101, v117, v101
	v_add_f32_e32 v2, v2, v2
	v_mul_f32_e32 v117, 0x3f4c422a, v117
	v_mul_f32_e32 v2, 0x3fb8aa3b, v2
	v_add_f32_e32 v117, v117, v117
	v_exp_f32_e32 v2, v2
	v_mul_f32_e32 v117, 0x3fb8aa3b, v117
	v_exp_f32_e32 v117, v117
	v_mul_f32_e32 v120, 0x3d372713, v103
	v_add_f32_e32 v2, 1.0, v2
	v_rcp_f32_e32 v118, v2
	v_add_f32_e32 v2, 1.0, v117
	v_rcp_f32_e32 v119, v2
	v_mul_f32_e32 v2, 0x3d372713, v102
	v_mul_f32_e32 v2, v102, v2
	v_fma_f32 v2, v102, v2, v102
	v_mul_f32_e32 v120, v103, v120
	v_mul_f32_e32 v2, 0x3f4c422a, v2
	v_fma_f32 v120, v103, v120, v103
	v_add_f32_e32 v2, v2, v2
	v_mul_f32_e32 v120, 0x3f4c422a, v120
	v_mul_f32_e32 v2, 0x3fb8aa3b, v2
	v_add_f32_e32 v120, v120, v120
	v_exp_f32_e32 v2, v2
	v_mul_f32_e32 v120, 0x3fb8aa3b, v120
	v_exp_f32_e32 v121, v120
	v_pk_fma_f32 v[118:119], v[118:119], 2.0, 1.0 op_sel_hi:[1,0,0] neg_lo:[1,0,0] neg_hi:[1,0,0]
	v_add_f32_e32 v2, 1.0, v2
	v_pk_mul_f32 v[100:101], v[100:101], 0.5 op_sel_hi:[1,0]
	v_rcp_f32_e32 v120, v2
	v_add_f32_e32 v2, 1.0, v121
	v_pk_add_f32 v[118:119], v[118:119], 1.0 op_sel_hi:[1,0]
	v_rcp_f32_e32 v121, v2
	v_pk_mul_f32 v[100:101], v[100:101], v[118:119]
	v_mul_f32_e32 v2, 0x3d372713, v104
	v_cvt_pk_bf16_f32 v100, v100, v101
	v_mul_f32_e32 v2, v104, v2
	v_mul_f32_e32 v101, 0x3d372713, v105
	v_fma_f32 v2, v104, v2, v104
	v_mul_f32_e32 v101, v105, v101
	v_mul_f32_e32 v2, 0x3f4c422a, v2
	v_fma_f32 v101, v105, v101, v105
	v_add_f32_e32 v2, v2, v2
	v_mul_f32_e32 v101, 0x3f4c422a, v101
	v_mul_f32_e32 v2, 0x3fb8aa3b, v2
	v_add_f32_e32 v101, v101, v101
	v_exp_f32_e32 v2, v2
	v_mul_f32_e32 v101, 0x3fb8aa3b, v101
	v_exp_f32_e32 v101, v101
	v_pk_fma_f32 v[118:119], v[120:121], 2.0, 1.0 op_sel_hi:[1,0,0] neg_lo:[1,0,0] neg_hi:[1,0,0]
	v_add_f32_e32 v2, 1.0, v2
	v_pk_mul_f32 v[102:103], v[102:103], 0.5 op_sel_hi:[1,0]
	v_pk_add_f32 v[118:119], v[118:119], 1.0 op_sel_hi:[1,0]
	v_rcp_f32_e32 v120, v2
	v_add_f32_e32 v2, 1.0, v101
	v_rcp_f32_e32 v121, v2
	v_pk_mul_f32 v[102:103], v[102:103], v[118:119]
	v_mul_f32_e32 v2, 0x3d372713, v106
	v_cvt_pk_bf16_f32 v101, v102, v103
	v_mul_f32_e32 v2, v106, v2
	v_mul_f32_e32 v102, 0x3d372713, v107
	v_fma_f32 v2, v106, v2, v106
	v_mul_f32_e32 v102, v107, v102
	v_mul_f32_e32 v2, 0x3f4c422a, v2
	v_fma_f32 v102, v107, v102, v107
	v_add_f32_e32 v2, v2, v2
	v_mul_f32_e32 v102, 0x3f4c422a, v102
	v_mul_f32_e32 v2, 0x3fb8aa3b, v2
	v_add_f32_e32 v102, v102, v102
	v_mov_b32_e32 v116, v183
	v_exp_f32_e32 v2, v2
	v_mul_f32_e32 v102, 0x3fb8aa3b, v102
	v_exp_f32_e32 v118, v102
	v_ashrrev_i32_e32 v117, 31, v116
	v_lshlrev_b64 v[116:117], 12, v[116:117]
	v_lshl_add_u64 v[116:117], v[196:197], 0, v[116:117]
	global_store_dwordx2 v[116:117], v[100:101], off
	v_pk_fma_f32 v[100:101], v[120:121], 2.0, 1.0 op_sel_hi:[1,0,0] neg_lo:[1,0,0] neg_hi:[1,0,0]
	v_add_f32_e32 v2, 1.0, v2
	v_pk_mul_f32 v[102:103], v[104:105], 0.5 op_sel_hi:[1,0]
	v_rcp_f32_e32 v104, v2
	v_add_f32_e32 v2, 1.0, v118
	v_pk_add_f32 v[100:101], v[100:101], 1.0 op_sel_hi:[1,0]
	v_rcp_f32_e32 v105, v2
	v_pk_mul_f32 v[100:101], v[102:103], v[100:101]
	v_mul_f32_e32 v2, 0x3d372713, v108
	v_cvt_pk_bf16_f32 v100, v100, v101
	v_mul_f32_e32 v2, v108, v2
	v_mul_f32_e32 v101, 0x3d372713, v109
	v_fma_f32 v2, v108, v2, v108
	v_mul_f32_e32 v101, v109, v101
	v_mul_f32_e32 v2, 0x3f4c422a, v2
	v_fma_f32 v101, v109, v101, v109
	v_add_f32_e32 v2, v2, v2
	v_mul_f32_e32 v101, 0x3f4c422a, v101
	v_mul_f32_e32 v2, 0x3fb8aa3b, v2
	v_add_f32_e32 v101, v101, v101
	v_exp_f32_e32 v2, v2
	v_mul_f32_e32 v101, 0x3fb8aa3b, v101
	v_exp_f32_e32 v101, v101
	v_pk_fma_f32 v[102:103], v[104:105], 2.0, 1.0 op_sel_hi:[1,0,0] neg_lo:[1,0,0] neg_hi:[1,0,0]
	v_add_f32_e32 v2, 1.0, v2
	v_pk_mul_f32 v[104:105], v[106:107], 0.5 op_sel_hi:[1,0]
	v_pk_add_f32 v[102:103], v[102:103], 1.0 op_sel_hi:[1,0]
	v_rcp_f32_e32 v106, v2
	v_add_f32_e32 v2, 1.0, v101
	v_rcp_f32_e32 v107, v2
	v_pk_mul_f32 v[102:103], v[104:105], v[102:103]
	v_mul_f32_e32 v2, 0x3d372713, v110
	v_cvt_pk_bf16_f32 v101, v102, v103
	v_mul_f32_e32 v2, v110, v2
	v_mul_f32_e32 v102, 0x3d372713, v111
	v_fma_f32 v2, v110, v2, v110
	v_mul_f32_e32 v102, v111, v102
	v_mul_f32_e32 v2, 0x3f4c422a, v2
	v_fma_f32 v102, v111, v102, v111
	v_add_f32_e32 v2, v2, v2
	v_mul_f32_e32 v102, 0x3f4c422a, v102
	v_mul_f32_e32 v2, 0x3fb8aa3b, v2
	v_add_f32_e32 v102, v102, v102
	v_exp_f32_e32 v2, v2
	v_mul_f32_e32 v102, 0x3fb8aa3b, v102
	v_exp_f32_e32 v105, v102
	global_store_dwordx2 v[116:117], v[100:101], off offset:16
	v_pk_fma_f32 v[100:101], v[106:107], 2.0, 1.0 op_sel_hi:[1,0,0] neg_lo:[1,0,0] neg_hi:[1,0,0]
	v_add_f32_e32 v2, 1.0, v2
	v_pk_mul_f32 v[102:103], v[108:109], 0.5 op_sel_hi:[1,0]
	v_rcp_f32_e32 v104, v2
	v_add_f32_e32 v2, 1.0, v105
	v_pk_add_f32 v[100:101], v[100:101], 1.0 op_sel_hi:[1,0]
	v_rcp_f32_e32 v105, v2
	v_pk_mul_f32 v[100:101], v[102:103], v[100:101]
	v_mul_f32_e32 v2, 0x3d372713, v112
	v_cvt_pk_bf16_f32 v100, v100, v101
	v_mul_f32_e32 v2, v112, v2
	v_mul_f32_e32 v101, 0x3d372713, v113
	v_fma_f32 v2, v112, v2, v112
	v_mul_f32_e32 v101, v113, v101
	v_mul_f32_e32 v2, 0x3f4c422a, v2
	v_fma_f32 v101, v113, v101, v113
	v_add_f32_e32 v2, v2, v2
	v_mul_f32_e32 v101, 0x3f4c422a, v101
	v_pk_fma_f32 v[102:103], v[104:105], 2.0, 1.0 op_sel_hi:[1,0,0] neg_lo:[1,0,0] neg_hi:[1,0,0]
	v_mul_f32_e32 v2, 0x3fb8aa3b, v2
	v_add_f32_e32 v101, v101, v101
	v_pk_mul_f32 v[104:105], v[110:111], 0.5 op_sel_hi:[1,0]
	v_pk_add_f32 v[102:103], v[102:103], 1.0 op_sel_hi:[1,0]
	v_exp_f32_e32 v2, v2
	v_mul_f32_e32 v101, 0x3fb8aa3b, v101
	v_pk_mul_f32 v[102:103], v[104:105], v[102:103]
	v_exp_f32_e32 v104, v101
	v_add_f32_e32 v2, 1.0, v2
	v_cvt_pk_bf16_f32 v101, v102, v103
	v_rcp_f32_e32 v102, v2
	v_add_f32_e32 v2, 1.0, v104
	v_rcp_f32_e32 v103, v2
	v_add_co_u32_e32 v104, vcc, s70, v116
	v_mul_f32_e32 v2, 0x3d372713, v114
	s_nop 0
	v_addc_co_u32_e32 v105, vcc, 0, v117, vcc
	global_store_dwordx2 v[104:105], v[100:101], off
	v_pk_fma_f32 v[100:101], v[102:103], 2.0, 1.0 op_sel_hi:[1,0,0] neg_lo:[1,0,0] neg_hi:[1,0,0]
	v_mul_f32_e32 v2, v114, v2
	v_mul_f32_e32 v102, 0x3d372713, v115
	v_fma_f32 v2, v114, v2, v114
	v_mul_f32_e32 v102, v115, v102
	v_mul_f32_e32 v2, 0x3f4c422a, v2
	v_fma_f32 v102, v115, v102, v115
	v_add_f32_e32 v2, v2, v2
	v_mul_f32_e32 v102, 0x3f4c422a, v102
	v_mul_f32_e32 v2, 0x3fb8aa3b, v2
	v_add_f32_e32 v102, v102, v102
	v_exp_f32_e32 v2, v2
	v_mul_f32_e32 v102, 0x3fb8aa3b, v102
	v_exp_f32_e32 v107, v102
	v_pk_mul_f32 v[102:103], v[112:113], 0.5 op_sel_hi:[1,0]
	v_add_f32_e32 v2, 1.0, v2
	v_rcp_f32_e32 v106, v2
	v_add_f32_e32 v2, 1.0, v107
	v_rcp_f32_e32 v107, v2
	v_pk_add_f32 v[100:101], v[100:101], 1.0 op_sel_hi:[1,0]
	s_nop 0
	v_pk_mul_f32 v[100:101], v[102:103], v[100:101]
	v_pk_fma_f32 v[102:103], v[106:107], 2.0, 1.0 op_sel_hi:[1,0,0] neg_lo:[1,0,0] neg_hi:[1,0,0]
	v_pk_mul_f32 v[106:107], v[114:115], 0.5 op_sel_hi:[1,0]
	v_pk_add_f32 v[102:103], v[102:103], 1.0 op_sel_hi:[1,0]
	v_cvt_pk_bf16_f32 v100, v100, v101
	v_pk_mul_f32 v[102:103], v[106:107], v[102:103]
	s_nop 0
	v_cvt_pk_bf16_f32 v101, v102, v103
	global_store_dwordx2 v[104:105], v[100:101], off offset:16
	v_mul_f32_e32 v2, 0x3d372713, v84
	v_mul_f32_e32 v2, v84, v2
	v_mul_f32_e32 v101, 0x3d372713, v85
	v_fma_f32 v2, v84, v2, v84
	v_mul_f32_e32 v101, v85, v101
	v_mul_f32_e32 v2, 0x3f4c422a, v2
	v_fma_f32 v101, v85, v101, v85
	v_add_f32_e32 v2, v2, v2
	v_mul_f32_e32 v101, 0x3f4c422a, v101
	v_mul_f32_e32 v2, 0x3fb8aa3b, v2
	v_add_f32_e32 v101, v101, v101
	v_exp_f32_e32 v2, v2
	v_mul_f32_e32 v101, 0x3fb8aa3b, v101
	v_exp_f32_e32 v101, v101
	v_mul_f32_e32 v104, 0x3d372713, v87
	v_add_f32_e32 v2, 1.0, v2
	v_rcp_f32_e32 v102, v2
	v_add_f32_e32 v2, 1.0, v101
	v_rcp_f32_e32 v103, v2
	v_mul_f32_e32 v2, 0x3d372713, v86
	v_mul_f32_e32 v2, v86, v2
	v_fma_f32 v2, v86, v2, v86
	v_mul_f32_e32 v104, v87, v104
	v_mul_f32_e32 v2, 0x3f4c422a, v2
	v_fma_f32 v104, v87, v104, v87
	v_add_f32_e32 v2, v2, v2
	v_mul_f32_e32 v104, 0x3f4c422a, v104
	v_mul_f32_e32 v2, 0x3fb8aa3b, v2
	v_add_f32_e32 v104, v104, v104
	v_exp_f32_e32 v2, v2
	v_mul_f32_e32 v104, 0x3fb8aa3b, v104
	v_exp_f32_e32 v105, v104
	v_pk_fma_f32 v[102:103], v[102:103], 2.0, 1.0 op_sel_hi:[1,0,0] neg_lo:[1,0,0] neg_hi:[1,0,0]
	v_add_f32_e32 v2, 1.0, v2
	v_pk_mul_f32 v[84:85], v[84:85], 0.5 op_sel_hi:[1,0]
	v_rcp_f32_e32 v104, v2
	v_add_f32_e32 v2, 1.0, v105
	v_pk_add_f32 v[102:103], v[102:103], 1.0 op_sel_hi:[1,0]
	v_rcp_f32_e32 v105, v2
	v_pk_mul_f32 v[84:85], v[84:85], v[102:103]
	v_mul_f32_e32 v2, 0x3d372713, v88
	v_cvt_pk_bf16_f32 v84, v84, v85
	v_mul_f32_e32 v2, v88, v2
	v_mul_f32_e32 v85, 0x3d372713, v89
	v_fma_f32 v2, v88, v2, v88
	v_mul_f32_e32 v85, v89, v85
	v_mul_f32_e32 v2, 0x3f4c422a, v2
	v_fma_f32 v85, v89, v85, v89
	v_add_f32_e32 v2, v2, v2
	v_mul_f32_e32 v85, 0x3f4c422a, v85
	v_mul_f32_e32 v2, 0x3fb8aa3b, v2
	v_add_f32_e32 v85, v85, v85
	v_exp_f32_e32 v2, v2
	v_mul_f32_e32 v85, 0x3fb8aa3b, v85
	v_exp_f32_e32 v85, v85
	v_pk_fma_f32 v[102:103], v[104:105], 2.0, 1.0 op_sel_hi:[1,0,0] neg_lo:[1,0,0] neg_hi:[1,0,0]
	v_add_f32_e32 v2, 1.0, v2
	v_pk_mul_f32 v[86:87], v[86:87], 0.5 op_sel_hi:[1,0]
	v_pk_add_f32 v[102:103], v[102:103], 1.0 op_sel_hi:[1,0]
	v_rcp_f32_e32 v104, v2
	v_add_f32_e32 v2, 1.0, v85
	v_rcp_f32_e32 v105, v2
	v_pk_mul_f32 v[86:87], v[86:87], v[102:103]
	v_mul_f32_e32 v2, 0x3d372713, v90
	v_cvt_pk_bf16_f32 v85, v86, v87
	v_mul_f32_e32 v2, v90, v2
	v_mul_f32_e32 v86, 0x3d372713, v91
	v_fma_f32 v2, v90, v2, v90
	v_mul_f32_e32 v86, v91, v86
	v_mul_f32_e32 v2, 0x3f4c422a, v2
	v_fma_f32 v86, v91, v86, v91
	v_add_f32_e32 v2, v2, v2
	v_mul_f32_e32 v86, 0x3f4c422a, v86
	v_mul_f32_e32 v2, 0x3fb8aa3b, v2
	v_add_f32_e32 v86, v86, v86
	v_mov_b32_e32 v100, v210
	v_exp_f32_e32 v2, v2
	v_mul_f32_e32 v86, 0x3fb8aa3b, v86
	v_exp_f32_e32 v102, v86
	v_ashrrev_i32_e32 v101, 31, v100
	v_lshlrev_b64 v[100:101], 12, v[100:101]
	v_lshl_add_u64 v[100:101], v[196:197], 0, v[100:101]
	global_store_dwordx2 v[100:101], v[84:85], off
	v_pk_fma_f32 v[84:85], v[104:105], 2.0, 1.0 op_sel_hi:[1,0,0] neg_lo:[1,0,0] neg_hi:[1,0,0]
	v_add_f32_e32 v2, 1.0, v2
	v_pk_mul_f32 v[86:87], v[88:89], 0.5 op_sel_hi:[1,0]
	v_rcp_f32_e32 v88, v2
	v_add_f32_e32 v2, 1.0, v102
	v_pk_add_f32 v[84:85], v[84:85], 1.0 op_sel_hi:[1,0]
	v_rcp_f32_e32 v89, v2
	v_pk_mul_f32 v[84:85], v[86:87], v[84:85]
	v_mul_f32_e32 v2, 0x3d372713, v92
	v_cvt_pk_bf16_f32 v84, v84, v85
	v_mul_f32_e32 v2, v92, v2
	v_mul_f32_e32 v85, 0x3d372713, v93
	v_fma_f32 v2, v92, v2, v92
	v_mul_f32_e32 v85, v93, v85
	v_mul_f32_e32 v2, 0x3f4c422a, v2
	v_fma_f32 v85, v93, v85, v93
	v_add_f32_e32 v2, v2, v2
	v_mul_f32_e32 v85, 0x3f4c422a, v85
	v_mul_f32_e32 v2, 0x3fb8aa3b, v2
	v_add_f32_e32 v85, v85, v85
	v_exp_f32_e32 v2, v2
	v_mul_f32_e32 v85, 0x3fb8aa3b, v85
	v_exp_f32_e32 v85, v85
	v_pk_fma_f32 v[86:87], v[88:89], 2.0, 1.0 op_sel_hi:[1,0,0] neg_lo:[1,0,0] neg_hi:[1,0,0]
	v_add_f32_e32 v2, 1.0, v2
	v_pk_mul_f32 v[88:89], v[90:91], 0.5 op_sel_hi:[1,0]
	v_pk_add_f32 v[86:87], v[86:87], 1.0 op_sel_hi:[1,0]
	v_rcp_f32_e32 v90, v2
	v_add_f32_e32 v2, 1.0, v85
	v_rcp_f32_e32 v91, v2
	v_pk_mul_f32 v[86:87], v[88:89], v[86:87]
	v_mul_f32_e32 v2, 0x3d372713, v94
	v_cvt_pk_bf16_f32 v85, v86, v87
	v_mul_f32_e32 v2, v94, v2
	v_mul_f32_e32 v86, 0x3d372713, v95
	v_fma_f32 v2, v94, v2, v94
	v_mul_f32_e32 v86, v95, v86
	v_mul_f32_e32 v2, 0x3f4c422a, v2
	v_fma_f32 v86, v95, v86, v95
	v_add_f32_e32 v2, v2, v2
	v_mul_f32_e32 v86, 0x3f4c422a, v86
	v_mul_f32_e32 v2, 0x3fb8aa3b, v2
	v_add_f32_e32 v86, v86, v86
	v_exp_f32_e32 v2, v2
	v_mul_f32_e32 v86, 0x3fb8aa3b, v86
	v_exp_f32_e32 v89, v86
	global_store_dwordx2 v[100:101], v[84:85], off offset:16
	v_pk_fma_f32 v[84:85], v[90:91], 2.0, 1.0 op_sel_hi:[1,0,0] neg_lo:[1,0,0] neg_hi:[1,0,0]
	v_add_f32_e32 v2, 1.0, v2
	v_pk_mul_f32 v[86:87], v[92:93], 0.5 op_sel_hi:[1,0]
	v_rcp_f32_e32 v88, v2
	v_add_f32_e32 v2, 1.0, v89
	v_pk_add_f32 v[84:85], v[84:85], 1.0 op_sel_hi:[1,0]
	v_rcp_f32_e32 v89, v2
	v_pk_mul_f32 v[84:85], v[86:87], v[84:85]
	v_mul_f32_e32 v2, 0x3d372713, v96
	v_cvt_pk_bf16_f32 v84, v84, v85
	v_mul_f32_e32 v2, v96, v2
	v_mul_f32_e32 v85, 0x3d372713, v97
	v_fma_f32 v2, v96, v2, v96
	v_mul_f32_e32 v85, v97, v85
	v_mul_f32_e32 v2, 0x3f4c422a, v2
	v_fma_f32 v85, v97, v85, v97
	v_add_f32_e32 v2, v2, v2
	v_mul_f32_e32 v85, 0x3f4c422a, v85
	v_pk_fma_f32 v[86:87], v[88:89], 2.0, 1.0 op_sel_hi:[1,0,0] neg_lo:[1,0,0] neg_hi:[1,0,0]
	v_mul_f32_e32 v2, 0x3fb8aa3b, v2
	v_add_f32_e32 v85, v85, v85
	v_pk_mul_f32 v[88:89], v[94:95], 0.5 op_sel_hi:[1,0]
	v_pk_add_f32 v[86:87], v[86:87], 1.0 op_sel_hi:[1,0]
	v_exp_f32_e32 v2, v2
	v_mul_f32_e32 v85, 0x3fb8aa3b, v85
	v_pk_mul_f32 v[86:87], v[88:89], v[86:87]
	v_exp_f32_e32 v88, v85
	v_add_f32_e32 v2, 1.0, v2
	v_cvt_pk_bf16_f32 v85, v86, v87
	v_rcp_f32_e32 v86, v2
	v_add_f32_e32 v2, 1.0, v88
	v_rcp_f32_e32 v87, v2
	v_add_co_u32_e32 v88, vcc, s70, v100
	v_mul_f32_e32 v2, 0x3d372713, v98
	s_nop 0
	v_addc_co_u32_e32 v89, vcc, 0, v101, vcc
	global_store_dwordx2 v[88:89], v[84:85], off
	v_pk_fma_f32 v[84:85], v[86:87], 2.0, 1.0 op_sel_hi:[1,0,0] neg_lo:[1,0,0] neg_hi:[1,0,0]
	v_mul_f32_e32 v2, v98, v2
	v_mul_f32_e32 v86, 0x3d372713, v99
	v_fma_f32 v2, v98, v2, v98
	v_mul_f32_e32 v86, v99, v86
	v_mul_f32_e32 v2, 0x3f4c422a, v2
	v_fma_f32 v86, v99, v86, v99
	v_add_f32_e32 v2, v2, v2
	v_mul_f32_e32 v86, 0x3f4c422a, v86
	v_mul_f32_e32 v2, 0x3fb8aa3b, v2
	v_add_f32_e32 v86, v86, v86
	v_exp_f32_e32 v2, v2
	v_mul_f32_e32 v86, 0x3fb8aa3b, v86
	v_exp_f32_e32 v91, v86
	v_pk_mul_f32 v[86:87], v[96:97], 0.5 op_sel_hi:[1,0]
	v_add_f32_e32 v2, 1.0, v2
	v_rcp_f32_e32 v90, v2
	v_add_f32_e32 v2, 1.0, v91
	v_rcp_f32_e32 v91, v2
	v_pk_add_f32 v[84:85], v[84:85], 1.0 op_sel_hi:[1,0]
	s_nop 0
	v_pk_mul_f32 v[84:85], v[86:87], v[84:85]
	v_pk_fma_f32 v[86:87], v[90:91], 2.0, 1.0 op_sel_hi:[1,0,0] neg_lo:[1,0,0] neg_hi:[1,0,0]
	v_pk_mul_f32 v[90:91], v[98:99], 0.5 op_sel_hi:[1,0]
	v_pk_add_f32 v[86:87], v[86:87], 1.0 op_sel_hi:[1,0]
	v_cvt_pk_bf16_f32 v84, v84, v85
	v_pk_mul_f32 v[86:87], v[90:91], v[86:87]
	s_nop 0
	v_cvt_pk_bf16_f32 v85, v86, v87
	global_store_dwordx2 v[88:89], v[84:85], off offset:16
	v_mul_f32_e32 v2, 0x3d372713, v68
	v_mul_f32_e32 v2, v68, v2
	v_mul_f32_e32 v85, 0x3d372713, v69
	v_fma_f32 v2, v68, v2, v68
	v_mul_f32_e32 v85, v69, v85
	v_mul_f32_e32 v2, 0x3f4c422a, v2
	v_fma_f32 v85, v69, v85, v69
	v_add_f32_e32 v2, v2, v2
	v_mul_f32_e32 v85, 0x3f4c422a, v85
	v_mul_f32_e32 v2, 0x3fb8aa3b, v2
	v_add_f32_e32 v85, v85, v85
	v_exp_f32_e32 v2, v2
	v_mul_f32_e32 v85, 0x3fb8aa3b, v85
	v_exp_f32_e32 v85, v85
	v_mul_f32_e32 v88, 0x3d372713, v71
	v_add_f32_e32 v2, 1.0, v2
	v_rcp_f32_e32 v86, v2
	v_add_f32_e32 v2, 1.0, v85
	v_rcp_f32_e32 v87, v2
	v_mul_f32_e32 v2, 0x3d372713, v70
	v_mul_f32_e32 v2, v70, v2
	v_fma_f32 v2, v70, v2, v70
	v_mul_f32_e32 v88, v71, v88
	v_mul_f32_e32 v2, 0x3f4c422a, v2
	v_fma_f32 v88, v71, v88, v71
	v_add_f32_e32 v2, v2, v2
	v_mul_f32_e32 v88, 0x3f4c422a, v88
	v_mul_f32_e32 v2, 0x3fb8aa3b, v2
	v_add_f32_e32 v88, v88, v88
	v_exp_f32_e32 v2, v2
	v_mul_f32_e32 v88, 0x3fb8aa3b, v88
	v_exp_f32_e32 v89, v88
	v_pk_fma_f32 v[86:87], v[86:87], 2.0, 1.0 op_sel_hi:[1,0,0] neg_lo:[1,0,0] neg_hi:[1,0,0]
	v_add_f32_e32 v2, 1.0, v2
	v_pk_mul_f32 v[68:69], v[68:69], 0.5 op_sel_hi:[1,0]
	v_rcp_f32_e32 v88, v2
	v_add_f32_e32 v2, 1.0, v89
	v_pk_add_f32 v[86:87], v[86:87], 1.0 op_sel_hi:[1,0]
	v_rcp_f32_e32 v89, v2
	v_pk_mul_f32 v[68:69], v[68:69], v[86:87]
	v_mul_f32_e32 v2, 0x3d372713, v72
	v_cvt_pk_bf16_f32 v68, v68, v69
	v_mul_f32_e32 v2, v72, v2
	v_mul_f32_e32 v69, 0x3d372713, v73
	v_fma_f32 v2, v72, v2, v72
	v_mul_f32_e32 v69, v73, v69
	v_mul_f32_e32 v2, 0x3f4c422a, v2
	v_fma_f32 v69, v73, v69, v73
	v_add_f32_e32 v2, v2, v2
	v_mul_f32_e32 v69, 0x3f4c422a, v69
	v_mul_f32_e32 v2, 0x3fb8aa3b, v2
	v_add_f32_e32 v69, v69, v69
	v_exp_f32_e32 v2, v2
	v_mul_f32_e32 v69, 0x3fb8aa3b, v69
	v_exp_f32_e32 v69, v69
	v_pk_fma_f32 v[86:87], v[88:89], 2.0, 1.0 op_sel_hi:[1,0,0] neg_lo:[1,0,0] neg_hi:[1,0,0]
	v_add_f32_e32 v2, 1.0, v2
	v_pk_mul_f32 v[70:71], v[70:71], 0.5 op_sel_hi:[1,0]
	v_pk_add_f32 v[86:87], v[86:87], 1.0 op_sel_hi:[1,0]
	v_rcp_f32_e32 v88, v2
	v_add_f32_e32 v2, 1.0, v69
	v_rcp_f32_e32 v89, v2
	v_pk_mul_f32 v[70:71], v[70:71], v[86:87]
	v_mul_f32_e32 v2, 0x3d372713, v74
	v_cvt_pk_bf16_f32 v69, v70, v71
	v_mul_f32_e32 v2, v74, v2
	v_mul_f32_e32 v70, 0x3d372713, v75
	v_fma_f32 v2, v74, v2, v74
	v_mul_f32_e32 v70, v75, v70
	v_mul_f32_e32 v2, 0x3f4c422a, v2
	v_fma_f32 v70, v75, v70, v75
	v_add_f32_e32 v2, v2, v2
	v_mul_f32_e32 v70, 0x3f4c422a, v70
	v_mul_f32_e32 v2, 0x3fb8aa3b, v2
	v_add_f32_e32 v70, v70, v70
	v_mov_b32_e32 v84, v211
	v_exp_f32_e32 v2, v2
	v_mul_f32_e32 v70, 0x3fb8aa3b, v70
	v_exp_f32_e32 v86, v70
	v_ashrrev_i32_e32 v85, 31, v84
	v_lshlrev_b64 v[84:85], 12, v[84:85]
	v_lshl_add_u64 v[84:85], v[196:197], 0, v[84:85]
	global_store_dwordx2 v[84:85], v[68:69], off
	v_pk_fma_f32 v[68:69], v[88:89], 2.0, 1.0 op_sel_hi:[1,0,0] neg_lo:[1,0,0] neg_hi:[1,0,0]
	v_add_f32_e32 v2, 1.0, v2
	v_pk_mul_f32 v[70:71], v[72:73], 0.5 op_sel_hi:[1,0]
	v_rcp_f32_e32 v72, v2
	v_add_f32_e32 v2, 1.0, v86
	v_pk_add_f32 v[68:69], v[68:69], 1.0 op_sel_hi:[1,0]
	v_rcp_f32_e32 v73, v2
	v_pk_mul_f32 v[68:69], v[70:71], v[68:69]
	v_mul_f32_e32 v2, 0x3d372713, v76
	v_cvt_pk_bf16_f32 v68, v68, v69
	v_mul_f32_e32 v2, v76, v2
	v_mul_f32_e32 v69, 0x3d372713, v77
	v_fma_f32 v2, v76, v2, v76
	v_mul_f32_e32 v69, v77, v69
	v_mul_f32_e32 v2, 0x3f4c422a, v2
	v_fma_f32 v69, v77, v69, v77
	v_add_f32_e32 v2, v2, v2
	v_mul_f32_e32 v69, 0x3f4c422a, v69
	v_mul_f32_e32 v2, 0x3fb8aa3b, v2
	v_add_f32_e32 v69, v69, v69
	v_exp_f32_e32 v2, v2
	v_mul_f32_e32 v69, 0x3fb8aa3b, v69
	v_exp_f32_e32 v69, v69
	v_pk_fma_f32 v[70:71], v[72:73], 2.0, 1.0 op_sel_hi:[1,0,0] neg_lo:[1,0,0] neg_hi:[1,0,0]
	v_add_f32_e32 v2, 1.0, v2
	v_pk_mul_f32 v[72:73], v[74:75], 0.5 op_sel_hi:[1,0]
	v_pk_add_f32 v[70:71], v[70:71], 1.0 op_sel_hi:[1,0]
	v_rcp_f32_e32 v74, v2
	v_add_f32_e32 v2, 1.0, v69
	v_rcp_f32_e32 v75, v2
	v_pk_mul_f32 v[70:71], v[72:73], v[70:71]
	v_mul_f32_e32 v2, 0x3d372713, v78
	v_cvt_pk_bf16_f32 v69, v70, v71
	v_mul_f32_e32 v2, v78, v2
	v_mul_f32_e32 v70, 0x3d372713, v79
	v_fma_f32 v2, v78, v2, v78
	v_mul_f32_e32 v70, v79, v70
	v_mul_f32_e32 v2, 0x3f4c422a, v2
	v_fma_f32 v70, v79, v70, v79
	v_add_f32_e32 v2, v2, v2
	v_mul_f32_e32 v70, 0x3f4c422a, v70
	v_mul_f32_e32 v2, 0x3fb8aa3b, v2
	v_add_f32_e32 v70, v70, v70
	v_exp_f32_e32 v2, v2
	v_mul_f32_e32 v70, 0x3fb8aa3b, v70
	v_exp_f32_e32 v73, v70
	global_store_dwordx2 v[84:85], v[68:69], off offset:16
	v_pk_fma_f32 v[68:69], v[74:75], 2.0, 1.0 op_sel_hi:[1,0,0] neg_lo:[1,0,0] neg_hi:[1,0,0]
	v_add_f32_e32 v2, 1.0, v2
	v_pk_mul_f32 v[70:71], v[76:77], 0.5 op_sel_hi:[1,0]
	v_rcp_f32_e32 v72, v2
	v_add_f32_e32 v2, 1.0, v73
	v_pk_add_f32 v[68:69], v[68:69], 1.0 op_sel_hi:[1,0]
	v_rcp_f32_e32 v73, v2
	v_pk_mul_f32 v[68:69], v[70:71], v[68:69]
	v_mul_f32_e32 v2, 0x3d372713, v80
	v_cvt_pk_bf16_f32 v68, v68, v69
	v_mul_f32_e32 v2, v80, v2
	v_mul_f32_e32 v69, 0x3d372713, v81
	v_fma_f32 v2, v80, v2, v80
	v_mul_f32_e32 v69, v81, v69
	v_mul_f32_e32 v2, 0x3f4c422a, v2
	v_fma_f32 v69, v81, v69, v81
	v_add_f32_e32 v2, v2, v2
	v_mul_f32_e32 v69, 0x3f4c422a, v69
	v_pk_fma_f32 v[70:71], v[72:73], 2.0, 1.0 op_sel_hi:[1,0,0] neg_lo:[1,0,0] neg_hi:[1,0,0]
	v_mul_f32_e32 v2, 0x3fb8aa3b, v2
	v_add_f32_e32 v69, v69, v69
	v_pk_mul_f32 v[72:73], v[78:79], 0.5 op_sel_hi:[1,0]
	v_pk_add_f32 v[70:71], v[70:71], 1.0 op_sel_hi:[1,0]
	v_exp_f32_e32 v2, v2
	v_mul_f32_e32 v69, 0x3fb8aa3b, v69
	v_pk_mul_f32 v[70:71], v[72:73], v[70:71]
	v_exp_f32_e32 v72, v69
	v_add_f32_e32 v2, 1.0, v2
	v_cvt_pk_bf16_f32 v69, v70, v71
	v_rcp_f32_e32 v70, v2
	v_add_f32_e32 v2, 1.0, v72
	v_rcp_f32_e32 v71, v2
	v_add_co_u32_e32 v72, vcc, s70, v84
	v_mul_f32_e32 v2, 0x3d372713, v82
	s_nop 0
	v_addc_co_u32_e32 v73, vcc, 0, v85, vcc
	global_store_dwordx2 v[72:73], v[68:69], off
	v_pk_fma_f32 v[68:69], v[70:71], 2.0, 1.0 op_sel_hi:[1,0,0] neg_lo:[1,0,0] neg_hi:[1,0,0]
	v_mul_f32_e32 v2, v82, v2
	v_mul_f32_e32 v70, 0x3d372713, v83
	v_fma_f32 v2, v82, v2, v82
	v_mul_f32_e32 v70, v83, v70
	v_mul_f32_e32 v2, 0x3f4c422a, v2
	v_fma_f32 v70, v83, v70, v83
	v_add_f32_e32 v2, v2, v2
	v_mul_f32_e32 v70, 0x3f4c422a, v70
	v_mul_f32_e32 v2, 0x3fb8aa3b, v2
	v_add_f32_e32 v70, v70, v70
	v_exp_f32_e32 v2, v2
	v_mul_f32_e32 v70, 0x3fb8aa3b, v70
	v_exp_f32_e32 v75, v70
	v_pk_mul_f32 v[70:71], v[80:81], 0.5 op_sel_hi:[1,0]
	v_add_f32_e32 v2, 1.0, v2
	v_rcp_f32_e32 v74, v2
	v_add_f32_e32 v2, 1.0, v75
	v_rcp_f32_e32 v75, v2
	v_pk_add_f32 v[68:69], v[68:69], 1.0 op_sel_hi:[1,0]
	s_nop 0
	v_pk_mul_f32 v[68:69], v[70:71], v[68:69]
	v_pk_fma_f32 v[70:71], v[74:75], 2.0, 1.0 op_sel_hi:[1,0,0] neg_lo:[1,0,0] neg_hi:[1,0,0]
	v_pk_mul_f32 v[74:75], v[82:83], 0.5 op_sel_hi:[1,0]
	v_pk_add_f32 v[70:71], v[70:71], 1.0 op_sel_hi:[1,0]
	v_cvt_pk_bf16_f32 v68, v68, v69
	v_pk_mul_f32 v[70:71], v[74:75], v[70:71]
	s_nop 0
	v_cvt_pk_bf16_f32 v69, v70, v71
	global_store_dwordx2 v[72:73], v[68:69], off offset:16
	v_mul_f32_e32 v2, 0x3d372713, v52
	v_mul_f32_e32 v2, v52, v2
	v_mul_f32_e32 v69, 0x3d372713, v53
	v_fma_f32 v2, v52, v2, v52
	v_mul_f32_e32 v69, v53, v69
	v_mul_f32_e32 v2, 0x3f4c422a, v2
	v_fma_f32 v69, v53, v69, v53
	v_add_f32_e32 v2, v2, v2
	v_mul_f32_e32 v69, 0x3f4c422a, v69
	v_mul_f32_e32 v2, 0x3fb8aa3b, v2
	v_add_f32_e32 v69, v69, v69
	v_exp_f32_e32 v2, v2
	v_mul_f32_e32 v69, 0x3fb8aa3b, v69
	v_exp_f32_e32 v69, v69
	v_mul_f32_e32 v72, 0x3d372713, v55
	v_add_f32_e32 v2, 1.0, v2
	v_rcp_f32_e32 v70, v2
	v_add_f32_e32 v2, 1.0, v69
	v_rcp_f32_e32 v71, v2
	v_mul_f32_e32 v2, 0x3d372713, v54
	v_mul_f32_e32 v2, v54, v2
	v_fma_f32 v2, v54, v2, v54
	v_mul_f32_e32 v72, v55, v72
	v_mul_f32_e32 v2, 0x3f4c422a, v2
	v_fma_f32 v72, v55, v72, v55
	v_add_f32_e32 v2, v2, v2
	v_mul_f32_e32 v72, 0x3f4c422a, v72
	v_mul_f32_e32 v2, 0x3fb8aa3b, v2
	v_add_f32_e32 v72, v72, v72
	v_exp_f32_e32 v2, v2
	v_mul_f32_e32 v72, 0x3fb8aa3b, v72
	v_exp_f32_e32 v73, v72
	v_pk_fma_f32 v[70:71], v[70:71], 2.0, 1.0 op_sel_hi:[1,0,0] neg_lo:[1,0,0] neg_hi:[1,0,0]
	v_add_f32_e32 v2, 1.0, v2
	v_pk_mul_f32 v[52:53], v[52:53], 0.5 op_sel_hi:[1,0]
	v_rcp_f32_e32 v72, v2
	v_add_f32_e32 v2, 1.0, v73
	v_pk_add_f32 v[70:71], v[70:71], 1.0 op_sel_hi:[1,0]
	v_rcp_f32_e32 v73, v2
	v_pk_mul_f32 v[52:53], v[52:53], v[70:71]
	v_mul_f32_e32 v2, 0x3d372713, v56
	v_cvt_pk_bf16_f32 v52, v52, v53
	v_mul_f32_e32 v2, v56, v2
	v_mul_f32_e32 v53, 0x3d372713, v57
	v_fma_f32 v2, v56, v2, v56
	v_mul_f32_e32 v53, v57, v53
	v_mul_f32_e32 v2, 0x3f4c422a, v2
	v_fma_f32 v53, v57, v53, v57
	v_add_f32_e32 v2, v2, v2
	v_mul_f32_e32 v53, 0x3f4c422a, v53
	v_mul_f32_e32 v2, 0x3fb8aa3b, v2
	v_add_f32_e32 v53, v53, v53
	v_exp_f32_e32 v2, v2
	v_mul_f32_e32 v53, 0x3fb8aa3b, v53
	v_exp_f32_e32 v53, v53
	v_pk_fma_f32 v[70:71], v[72:73], 2.0, 1.0 op_sel_hi:[1,0,0] neg_lo:[1,0,0] neg_hi:[1,0,0]
	v_add_f32_e32 v2, 1.0, v2
	v_pk_mul_f32 v[54:55], v[54:55], 0.5 op_sel_hi:[1,0]
	v_pk_add_f32 v[70:71], v[70:71], 1.0 op_sel_hi:[1,0]
	v_rcp_f32_e32 v72, v2
	v_add_f32_e32 v2, 1.0, v53
	v_rcp_f32_e32 v73, v2
	v_pk_mul_f32 v[54:55], v[54:55], v[70:71]
	v_mul_f32_e32 v2, 0x3d372713, v58
	v_cvt_pk_bf16_f32 v53, v54, v55
	v_mul_f32_e32 v2, v58, v2
	v_mul_f32_e32 v54, 0x3d372713, v59
	v_fma_f32 v2, v58, v2, v58
	v_mul_f32_e32 v54, v59, v54
	v_mul_f32_e32 v2, 0x3f4c422a, v2
	v_fma_f32 v54, v59, v54, v59
	v_add_f32_e32 v2, v2, v2
	v_mul_f32_e32 v54, 0x3f4c422a, v54
	v_mul_f32_e32 v2, 0x3fb8aa3b, v2
	v_add_f32_e32 v54, v54, v54
	v_mov_b32_e32 v68, v212
	v_exp_f32_e32 v2, v2
	v_mul_f32_e32 v54, 0x3fb8aa3b, v54
	v_exp_f32_e32 v70, v54
	v_ashrrev_i32_e32 v69, 31, v68
	v_lshlrev_b64 v[68:69], 12, v[68:69]
	v_lshl_add_u64 v[68:69], v[196:197], 0, v[68:69]
	global_store_dwordx2 v[68:69], v[52:53], off
	v_pk_fma_f32 v[52:53], v[72:73], 2.0, 1.0 op_sel_hi:[1,0,0] neg_lo:[1,0,0] neg_hi:[1,0,0]
	v_add_f32_e32 v2, 1.0, v2
	v_pk_mul_f32 v[54:55], v[56:57], 0.5 op_sel_hi:[1,0]
	v_rcp_f32_e32 v56, v2
	v_add_f32_e32 v2, 1.0, v70
	v_pk_add_f32 v[52:53], v[52:53], 1.0 op_sel_hi:[1,0]
	v_rcp_f32_e32 v57, v2
	v_pk_mul_f32 v[52:53], v[54:55], v[52:53]
	v_mul_f32_e32 v2, 0x3d372713, v60
	v_cvt_pk_bf16_f32 v52, v52, v53
	v_mul_f32_e32 v2, v60, v2
	v_mul_f32_e32 v53, 0x3d372713, v61
	v_fma_f32 v2, v60, v2, v60
	v_mul_f32_e32 v53, v61, v53
	v_mul_f32_e32 v2, 0x3f4c422a, v2
	v_fma_f32 v53, v61, v53, v61
	v_add_f32_e32 v2, v2, v2
	v_mul_f32_e32 v53, 0x3f4c422a, v53
	v_mul_f32_e32 v2, 0x3fb8aa3b, v2
	v_add_f32_e32 v53, v53, v53
	v_exp_f32_e32 v2, v2
	v_mul_f32_e32 v53, 0x3fb8aa3b, v53
	v_exp_f32_e32 v53, v53
	v_pk_fma_f32 v[54:55], v[56:57], 2.0, 1.0 op_sel_hi:[1,0,0] neg_lo:[1,0,0] neg_hi:[1,0,0]
	v_add_f32_e32 v2, 1.0, v2
	v_pk_mul_f32 v[56:57], v[58:59], 0.5 op_sel_hi:[1,0]
	v_pk_add_f32 v[54:55], v[54:55], 1.0 op_sel_hi:[1,0]
	v_rcp_f32_e32 v58, v2
	v_add_f32_e32 v2, 1.0, v53
	v_rcp_f32_e32 v59, v2
	v_pk_mul_f32 v[54:55], v[56:57], v[54:55]
	v_mul_f32_e32 v2, 0x3d372713, v62
	v_cvt_pk_bf16_f32 v53, v54, v55
	v_mul_f32_e32 v2, v62, v2
	v_mul_f32_e32 v54, 0x3d372713, v63
	v_fma_f32 v2, v62, v2, v62
	v_mul_f32_e32 v54, v63, v54
	v_mul_f32_e32 v2, 0x3f4c422a, v2
	v_fma_f32 v54, v63, v54, v63
	v_add_f32_e32 v2, v2, v2
	v_mul_f32_e32 v54, 0x3f4c422a, v54
	v_mul_f32_e32 v2, 0x3fb8aa3b, v2
	v_add_f32_e32 v54, v54, v54
	v_exp_f32_e32 v2, v2
	v_mul_f32_e32 v54, 0x3fb8aa3b, v54
	v_exp_f32_e32 v57, v54
	global_store_dwordx2 v[68:69], v[52:53], off offset:16
	v_pk_fma_f32 v[52:53], v[58:59], 2.0, 1.0 op_sel_hi:[1,0,0] neg_lo:[1,0,0] neg_hi:[1,0,0]
	v_add_f32_e32 v2, 1.0, v2
	v_pk_mul_f32 v[54:55], v[60:61], 0.5 op_sel_hi:[1,0]
	v_rcp_f32_e32 v56, v2
	v_add_f32_e32 v2, 1.0, v57
	v_pk_add_f32 v[52:53], v[52:53], 1.0 op_sel_hi:[1,0]
	v_rcp_f32_e32 v57, v2
	v_pk_mul_f32 v[52:53], v[54:55], v[52:53]
	v_mul_f32_e32 v2, 0x3d372713, v64
	v_cvt_pk_bf16_f32 v52, v52, v53
	v_mul_f32_e32 v2, v64, v2
	v_mul_f32_e32 v53, 0x3d372713, v65
	v_fma_f32 v2, v64, v2, v64
	v_mul_f32_e32 v53, v65, v53
	v_mul_f32_e32 v2, 0x3f4c422a, v2
	v_fma_f32 v53, v65, v53, v65
	v_add_f32_e32 v2, v2, v2
	v_mul_f32_e32 v53, 0x3f4c422a, v53
	v_pk_fma_f32 v[54:55], v[56:57], 2.0, 1.0 op_sel_hi:[1,0,0] neg_lo:[1,0,0] neg_hi:[1,0,0]
	v_mul_f32_e32 v2, 0x3fb8aa3b, v2
	v_add_f32_e32 v53, v53, v53
	v_pk_mul_f32 v[56:57], v[62:63], 0.5 op_sel_hi:[1,0]
	v_pk_add_f32 v[54:55], v[54:55], 1.0 op_sel_hi:[1,0]
	v_exp_f32_e32 v2, v2
	v_mul_f32_e32 v53, 0x3fb8aa3b, v53
	v_pk_mul_f32 v[54:55], v[56:57], v[54:55]
	v_exp_f32_e32 v56, v53
	v_add_f32_e32 v2, 1.0, v2
	v_cvt_pk_bf16_f32 v53, v54, v55
	v_rcp_f32_e32 v54, v2
	v_add_f32_e32 v2, 1.0, v56
	v_rcp_f32_e32 v55, v2
	v_add_co_u32_e32 v56, vcc, s70, v68
	v_mul_f32_e32 v2, 0x3d372713, v66
	s_nop 0
	v_addc_co_u32_e32 v57, vcc, 0, v69, vcc
	global_store_dwordx2 v[56:57], v[52:53], off
	v_pk_fma_f32 v[52:53], v[54:55], 2.0, 1.0 op_sel_hi:[1,0,0] neg_lo:[1,0,0] neg_hi:[1,0,0]
	v_mul_f32_e32 v2, v66, v2
	v_mul_f32_e32 v54, 0x3d372713, v67
	v_fma_f32 v2, v66, v2, v66
	v_mul_f32_e32 v54, v67, v54
	v_mul_f32_e32 v2, 0x3f4c422a, v2
	v_fma_f32 v54, v67, v54, v67
	v_add_f32_e32 v2, v2, v2
	v_mul_f32_e32 v54, 0x3f4c422a, v54
	v_mul_f32_e32 v2, 0x3fb8aa3b, v2
	v_add_f32_e32 v54, v54, v54
	v_exp_f32_e32 v2, v2
	v_mul_f32_e32 v54, 0x3fb8aa3b, v54
	v_exp_f32_e32 v59, v54
	v_pk_mul_f32 v[54:55], v[64:65], 0.5 op_sel_hi:[1,0]
	v_add_f32_e32 v2, 1.0, v2
	v_rcp_f32_e32 v58, v2
	v_add_f32_e32 v2, 1.0, v59
	v_rcp_f32_e32 v59, v2
	v_pk_add_f32 v[52:53], v[52:53], 1.0 op_sel_hi:[1,0]
	s_nop 0
	v_pk_mul_f32 v[52:53], v[54:55], v[52:53]
	v_pk_fma_f32 v[54:55], v[58:59], 2.0, 1.0 op_sel_hi:[1,0,0] neg_lo:[1,0,0] neg_hi:[1,0,0]
	v_pk_mul_f32 v[58:59], v[66:67], 0.5 op_sel_hi:[1,0]
	v_pk_add_f32 v[54:55], v[54:55], 1.0 op_sel_hi:[1,0]
	v_cvt_pk_bf16_f32 v52, v52, v53
	v_pk_mul_f32 v[54:55], v[58:59], v[54:55]
	s_nop 0
	v_cvt_pk_bf16_f32 v53, v54, v55
	global_store_dwordx2 v[56:57], v[52:53], off offset:16
	v_mul_f32_e32 v2, 0x3d372713, v36
	v_mul_f32_e32 v2, v36, v2
	v_mul_f32_e32 v53, 0x3d372713, v37
	v_fma_f32 v2, v36, v2, v36
	v_mul_f32_e32 v53, v37, v53
	v_mul_f32_e32 v2, 0x3f4c422a, v2
	v_fma_f32 v53, v37, v53, v37
	v_add_f32_e32 v2, v2, v2
	v_mul_f32_e32 v53, 0x3f4c422a, v53
	v_mul_f32_e32 v2, 0x3fb8aa3b, v2
	v_add_f32_e32 v53, v53, v53
	v_exp_f32_e32 v2, v2
	v_mul_f32_e32 v53, 0x3fb8aa3b, v53
	v_exp_f32_e32 v53, v53
	v_mul_f32_e32 v56, 0x3d372713, v39
	v_add_f32_e32 v2, 1.0, v2
	v_rcp_f32_e32 v54, v2
	v_add_f32_e32 v2, 1.0, v53
	v_rcp_f32_e32 v55, v2
	v_mul_f32_e32 v2, 0x3d372713, v38
	v_mul_f32_e32 v2, v38, v2
	v_fma_f32 v2, v38, v2, v38
	v_mul_f32_e32 v56, v39, v56
	v_mul_f32_e32 v2, 0x3f4c422a, v2
	v_fma_f32 v56, v39, v56, v39
	v_add_f32_e32 v2, v2, v2
	v_mul_f32_e32 v56, 0x3f4c422a, v56
	v_mul_f32_e32 v2, 0x3fb8aa3b, v2
	v_add_f32_e32 v56, v56, v56
	v_exp_f32_e32 v2, v2
	v_mul_f32_e32 v56, 0x3fb8aa3b, v56
	v_exp_f32_e32 v57, v56
	v_pk_fma_f32 v[54:55], v[54:55], 2.0, 1.0 op_sel_hi:[1,0,0] neg_lo:[1,0,0] neg_hi:[1,0,0]
	v_add_f32_e32 v2, 1.0, v2
	v_pk_mul_f32 v[36:37], v[36:37], 0.5 op_sel_hi:[1,0]
	v_rcp_f32_e32 v56, v2
	v_add_f32_e32 v2, 1.0, v57
	v_pk_add_f32 v[54:55], v[54:55], 1.0 op_sel_hi:[1,0]
	v_rcp_f32_e32 v57, v2
	v_pk_mul_f32 v[36:37], v[36:37], v[54:55]
	v_mul_f32_e32 v2, 0x3d372713, v40
	v_cvt_pk_bf16_f32 v36, v36, v37
	v_mul_f32_e32 v2, v40, v2
	v_mul_f32_e32 v37, 0x3d372713, v41
	v_fma_f32 v2, v40, v2, v40
	v_mul_f32_e32 v37, v41, v37
	v_mul_f32_e32 v2, 0x3f4c422a, v2
	v_fma_f32 v37, v41, v37, v41
	v_add_f32_e32 v2, v2, v2
	v_mul_f32_e32 v37, 0x3f4c422a, v37
	v_mul_f32_e32 v2, 0x3fb8aa3b, v2
	v_add_f32_e32 v37, v37, v37
	v_exp_f32_e32 v2, v2
	v_mul_f32_e32 v37, 0x3fb8aa3b, v37
	v_exp_f32_e32 v37, v37
	v_pk_fma_f32 v[54:55], v[56:57], 2.0, 1.0 op_sel_hi:[1,0,0] neg_lo:[1,0,0] neg_hi:[1,0,0]
	v_add_f32_e32 v2, 1.0, v2
	v_pk_mul_f32 v[38:39], v[38:39], 0.5 op_sel_hi:[1,0]
	v_pk_add_f32 v[54:55], v[54:55], 1.0 op_sel_hi:[1,0]
	v_rcp_f32_e32 v56, v2
	v_add_f32_e32 v2, 1.0, v37
	v_rcp_f32_e32 v57, v2
	v_pk_mul_f32 v[38:39], v[38:39], v[54:55]
	v_mul_f32_e32 v2, 0x3d372713, v42
	v_cvt_pk_bf16_f32 v37, v38, v39
	v_mul_f32_e32 v2, v42, v2
	v_mul_f32_e32 v38, 0x3d372713, v43
	v_fma_f32 v2, v42, v2, v42
	v_mul_f32_e32 v38, v43, v38
	v_mul_f32_e32 v2, 0x3f4c422a, v2
	v_fma_f32 v38, v43, v38, v43
	v_add_f32_e32 v2, v2, v2
	v_mul_f32_e32 v38, 0x3f4c422a, v38
	v_mul_f32_e32 v2, 0x3fb8aa3b, v2
	v_add_f32_e32 v38, v38, v38
	v_mov_b32_e32 v52, v213
	v_exp_f32_e32 v2, v2
	v_mul_f32_e32 v38, 0x3fb8aa3b, v38
	v_exp_f32_e32 v54, v38
	v_ashrrev_i32_e32 v53, 31, v52
	v_lshlrev_b64 v[52:53], 12, v[52:53]
	v_lshl_add_u64 v[52:53], v[196:197], 0, v[52:53]
	global_store_dwordx2 v[52:53], v[36:37], off
	v_pk_fma_f32 v[36:37], v[56:57], 2.0, 1.0 op_sel_hi:[1,0,0] neg_lo:[1,0,0] neg_hi:[1,0,0]
	v_add_f32_e32 v2, 1.0, v2
	v_pk_mul_f32 v[38:39], v[40:41], 0.5 op_sel_hi:[1,0]
	v_rcp_f32_e32 v40, v2
	v_add_f32_e32 v2, 1.0, v54
	v_pk_add_f32 v[36:37], v[36:37], 1.0 op_sel_hi:[1,0]
	v_rcp_f32_e32 v41, v2
	v_pk_mul_f32 v[36:37], v[38:39], v[36:37]
	v_mul_f32_e32 v2, 0x3d372713, v44
	v_cvt_pk_bf16_f32 v36, v36, v37
	v_mul_f32_e32 v2, v44, v2
	v_mul_f32_e32 v37, 0x3d372713, v45
	v_fma_f32 v2, v44, v2, v44
	v_mul_f32_e32 v37, v45, v37
	v_mul_f32_e32 v2, 0x3f4c422a, v2
	v_fma_f32 v37, v45, v37, v45
	v_add_f32_e32 v2, v2, v2
	v_mul_f32_e32 v37, 0x3f4c422a, v37
	v_mul_f32_e32 v2, 0x3fb8aa3b, v2
	v_add_f32_e32 v37, v37, v37
	v_exp_f32_e32 v2, v2
	v_mul_f32_e32 v37, 0x3fb8aa3b, v37
	v_exp_f32_e32 v37, v37
	v_pk_fma_f32 v[38:39], v[40:41], 2.0, 1.0 op_sel_hi:[1,0,0] neg_lo:[1,0,0] neg_hi:[1,0,0]
	v_add_f32_e32 v2, 1.0, v2
	v_pk_mul_f32 v[40:41], v[42:43], 0.5 op_sel_hi:[1,0]
	v_pk_add_f32 v[38:39], v[38:39], 1.0 op_sel_hi:[1,0]
	v_rcp_f32_e32 v42, v2
	v_add_f32_e32 v2, 1.0, v37
	v_rcp_f32_e32 v43, v2
	v_pk_mul_f32 v[38:39], v[40:41], v[38:39]
	v_mul_f32_e32 v2, 0x3d372713, v46
	v_cvt_pk_bf16_f32 v37, v38, v39
	v_mul_f32_e32 v2, v46, v2
	v_mul_f32_e32 v38, 0x3d372713, v47
	v_fma_f32 v2, v46, v2, v46
	v_mul_f32_e32 v38, v47, v38
	v_mul_f32_e32 v2, 0x3f4c422a, v2
	v_fma_f32 v38, v47, v38, v47
	v_add_f32_e32 v2, v2, v2
	v_mul_f32_e32 v38, 0x3f4c422a, v38
	v_mul_f32_e32 v2, 0x3fb8aa3b, v2
	v_add_f32_e32 v38, v38, v38
	v_exp_f32_e32 v2, v2
	v_mul_f32_e32 v38, 0x3fb8aa3b, v38
	v_exp_f32_e32 v41, v38
	global_store_dwordx2 v[52:53], v[36:37], off offset:16
	v_pk_fma_f32 v[36:37], v[42:43], 2.0, 1.0 op_sel_hi:[1,0,0] neg_lo:[1,0,0] neg_hi:[1,0,0]
	v_add_f32_e32 v2, 1.0, v2
	v_pk_mul_f32 v[38:39], v[44:45], 0.5 op_sel_hi:[1,0]
	v_rcp_f32_e32 v40, v2
	v_add_f32_e32 v2, 1.0, v41
	v_pk_add_f32 v[36:37], v[36:37], 1.0 op_sel_hi:[1,0]
	v_rcp_f32_e32 v41, v2
	v_pk_mul_f32 v[36:37], v[38:39], v[36:37]
	v_mul_f32_e32 v2, 0x3d372713, v48
	v_cvt_pk_bf16_f32 v36, v36, v37
	v_mul_f32_e32 v2, v48, v2
	v_mul_f32_e32 v37, 0x3d372713, v49
	v_fma_f32 v2, v48, v2, v48
	v_mul_f32_e32 v37, v49, v37
	v_mul_f32_e32 v2, 0x3f4c422a, v2
	v_fma_f32 v37, v49, v37, v49
	v_add_f32_e32 v2, v2, v2
	v_mul_f32_e32 v37, 0x3f4c422a, v37
	v_pk_fma_f32 v[38:39], v[40:41], 2.0, 1.0 op_sel_hi:[1,0,0] neg_lo:[1,0,0] neg_hi:[1,0,0]
	v_mul_f32_e32 v2, 0x3fb8aa3b, v2
	v_add_f32_e32 v37, v37, v37
	v_pk_mul_f32 v[40:41], v[46:47], 0.5 op_sel_hi:[1,0]
	v_pk_add_f32 v[38:39], v[38:39], 1.0 op_sel_hi:[1,0]
	v_exp_f32_e32 v2, v2
	v_mul_f32_e32 v37, 0x3fb8aa3b, v37
	v_pk_mul_f32 v[38:39], v[40:41], v[38:39]
	v_exp_f32_e32 v40, v37
	v_add_f32_e32 v2, 1.0, v2
	v_cvt_pk_bf16_f32 v37, v38, v39
	v_rcp_f32_e32 v38, v2
	v_add_f32_e32 v2, 1.0, v40
	v_rcp_f32_e32 v39, v2
	v_add_co_u32_e32 v40, vcc, s70, v52
	v_mul_f32_e32 v2, 0x3d372713, v50
	s_nop 0
	v_addc_co_u32_e32 v41, vcc, 0, v53, vcc
	global_store_dwordx2 v[40:41], v[36:37], off
	v_pk_fma_f32 v[36:37], v[38:39], 2.0, 1.0 op_sel_hi:[1,0,0] neg_lo:[1,0,0] neg_hi:[1,0,0]
	v_mul_f32_e32 v2, v50, v2
	v_mul_f32_e32 v38, 0x3d372713, v51
	v_fma_f32 v2, v50, v2, v50
	v_mul_f32_e32 v38, v51, v38
	v_mul_f32_e32 v2, 0x3f4c422a, v2
	v_fma_f32 v38, v51, v38, v51
	v_add_f32_e32 v2, v2, v2
	v_mul_f32_e32 v38, 0x3f4c422a, v38
	v_mul_f32_e32 v2, 0x3fb8aa3b, v2
	v_add_f32_e32 v38, v38, v38
	v_exp_f32_e32 v2, v2
	v_mul_f32_e32 v38, 0x3fb8aa3b, v38
	v_exp_f32_e32 v43, v38
	v_pk_mul_f32 v[38:39], v[48:49], 0.5 op_sel_hi:[1,0]
	v_add_f32_e32 v2, 1.0, v2
	v_rcp_f32_e32 v42, v2
	v_add_f32_e32 v2, 1.0, v43
	v_rcp_f32_e32 v43, v2
	v_pk_add_f32 v[36:37], v[36:37], 1.0 op_sel_hi:[1,0]
	s_nop 0
	v_pk_mul_f32 v[36:37], v[38:39], v[36:37]
	v_pk_fma_f32 v[38:39], v[42:43], 2.0, 1.0 op_sel_hi:[1,0,0] neg_lo:[1,0,0] neg_hi:[1,0,0]
	v_pk_mul_f32 v[42:43], v[50:51], 0.5 op_sel_hi:[1,0]
	v_pk_add_f32 v[38:39], v[38:39], 1.0 op_sel_hi:[1,0]
	v_cvt_pk_bf16_f32 v36, v36, v37
	v_pk_mul_f32 v[38:39], v[42:43], v[38:39]
	s_nop 0
	v_cvt_pk_bf16_f32 v37, v38, v39
	global_store_dwordx2 v[40:41], v[36:37], off offset:16
	v_mul_f32_e32 v2, 0x3d372713, v20
	v_mul_f32_e32 v2, v20, v2
	v_mul_f32_e32 v37, 0x3d372713, v21
	v_fma_f32 v2, v20, v2, v20
	v_mul_f32_e32 v37, v21, v37
	v_mul_f32_e32 v2, 0x3f4c422a, v2
	v_fma_f32 v37, v21, v37, v21
	v_add_f32_e32 v2, v2, v2
	v_mul_f32_e32 v37, 0x3f4c422a, v37
	v_mul_f32_e32 v2, 0x3fb8aa3b, v2
	v_add_f32_e32 v37, v37, v37
	v_exp_f32_e32 v2, v2
	v_mul_f32_e32 v37, 0x3fb8aa3b, v37
	v_exp_f32_e32 v37, v37
	v_mul_f32_e32 v40, 0x3d372713, v23
	v_add_f32_e32 v2, 1.0, v2
	v_rcp_f32_e32 v38, v2
	v_add_f32_e32 v2, 1.0, v37
	v_rcp_f32_e32 v39, v2
	v_mul_f32_e32 v2, 0x3d372713, v22
	v_mul_f32_e32 v2, v22, v2
	v_fma_f32 v2, v22, v2, v22
	v_mul_f32_e32 v40, v23, v40
	v_mul_f32_e32 v2, 0x3f4c422a, v2
	v_fma_f32 v40, v23, v40, v23
	v_add_f32_e32 v2, v2, v2
	v_mul_f32_e32 v40, 0x3f4c422a, v40
	v_mul_f32_e32 v2, 0x3fb8aa3b, v2
	v_add_f32_e32 v40, v40, v40
	v_exp_f32_e32 v2, v2
	v_mul_f32_e32 v40, 0x3fb8aa3b, v40
	v_exp_f32_e32 v41, v40
	v_pk_fma_f32 v[38:39], v[38:39], 2.0, 1.0 op_sel_hi:[1,0,0] neg_lo:[1,0,0] neg_hi:[1,0,0]
	v_add_f32_e32 v2, 1.0, v2
	v_pk_mul_f32 v[20:21], v[20:21], 0.5 op_sel_hi:[1,0]
	v_rcp_f32_e32 v40, v2
	v_add_f32_e32 v2, 1.0, v41
	v_pk_add_f32 v[38:39], v[38:39], 1.0 op_sel_hi:[1,0]
	v_rcp_f32_e32 v41, v2
	v_pk_mul_f32 v[20:21], v[20:21], v[38:39]
	v_mul_f32_e32 v2, 0x3d372713, v24
	v_cvt_pk_bf16_f32 v20, v20, v21
	v_mul_f32_e32 v2, v24, v2
	v_mul_f32_e32 v21, 0x3d372713, v25
	v_fma_f32 v2, v24, v2, v24
	v_mul_f32_e32 v21, v25, v21
	v_mul_f32_e32 v2, 0x3f4c422a, v2
	v_fma_f32 v21, v25, v21, v25
	v_add_f32_e32 v2, v2, v2
	v_mul_f32_e32 v21, 0x3f4c422a, v21
	v_mul_f32_e32 v2, 0x3fb8aa3b, v2
	v_add_f32_e32 v21, v21, v21
	v_exp_f32_e32 v2, v2
	v_mul_f32_e32 v21, 0x3fb8aa3b, v21
	v_exp_f32_e32 v21, v21
	v_pk_fma_f32 v[38:39], v[40:41], 2.0, 1.0 op_sel_hi:[1,0,0] neg_lo:[1,0,0] neg_hi:[1,0,0]
	v_add_f32_e32 v2, 1.0, v2
	v_pk_mul_f32 v[22:23], v[22:23], 0.5 op_sel_hi:[1,0]
	v_pk_add_f32 v[38:39], v[38:39], 1.0 op_sel_hi:[1,0]
	v_rcp_f32_e32 v40, v2
	v_add_f32_e32 v2, 1.0, v21
	v_rcp_f32_e32 v41, v2
	v_pk_mul_f32 v[22:23], v[22:23], v[38:39]
	v_mul_f32_e32 v2, 0x3d372713, v26
	v_cvt_pk_bf16_f32 v21, v22, v23
	v_mul_f32_e32 v2, v26, v2
	v_mul_f32_e32 v22, 0x3d372713, v27
	v_fma_f32 v2, v26, v2, v26
	v_mul_f32_e32 v22, v27, v22
	v_mul_f32_e32 v2, 0x3f4c422a, v2
	v_fma_f32 v22, v27, v22, v27
	v_add_f32_e32 v2, v2, v2
	v_mul_f32_e32 v22, 0x3f4c422a, v22
	v_mul_f32_e32 v2, 0x3fb8aa3b, v2
	v_add_f32_e32 v22, v22, v22
	v_mov_b32_e32 v36, v214
	v_exp_f32_e32 v2, v2
	v_mul_f32_e32 v22, 0x3fb8aa3b, v22
	v_exp_f32_e32 v38, v22
	v_ashrrev_i32_e32 v37, 31, v36
	v_lshlrev_b64 v[36:37], 12, v[36:37]
	v_lshl_add_u64 v[36:37], v[196:197], 0, v[36:37]
	global_store_dwordx2 v[36:37], v[20:21], off
	v_pk_fma_f32 v[20:21], v[40:41], 2.0, 1.0 op_sel_hi:[1,0,0] neg_lo:[1,0,0] neg_hi:[1,0,0]
	v_add_f32_e32 v2, 1.0, v2
	v_pk_mul_f32 v[22:23], v[24:25], 0.5 op_sel_hi:[1,0]
	v_rcp_f32_e32 v24, v2
	v_add_f32_e32 v2, 1.0, v38
	v_pk_add_f32 v[20:21], v[20:21], 1.0 op_sel_hi:[1,0]
	v_rcp_f32_e32 v25, v2
	v_pk_mul_f32 v[20:21], v[22:23], v[20:21]
	v_mul_f32_e32 v2, 0x3d372713, v28
	v_cvt_pk_bf16_f32 v20, v20, v21
	v_mul_f32_e32 v2, v28, v2
	v_mul_f32_e32 v21, 0x3d372713, v29
	v_fma_f32 v2, v28, v2, v28
	v_mul_f32_e32 v21, v29, v21
	v_mul_f32_e32 v2, 0x3f4c422a, v2
	v_fma_f32 v21, v29, v21, v29
	v_add_f32_e32 v2, v2, v2
	v_mul_f32_e32 v21, 0x3f4c422a, v21
	v_mul_f32_e32 v2, 0x3fb8aa3b, v2
	v_add_f32_e32 v21, v21, v21
	v_exp_f32_e32 v2, v2
	v_mul_f32_e32 v21, 0x3fb8aa3b, v21
	v_exp_f32_e32 v21, v21
	v_pk_fma_f32 v[22:23], v[24:25], 2.0, 1.0 op_sel_hi:[1,0,0] neg_lo:[1,0,0] neg_hi:[1,0,0]
	v_add_f32_e32 v2, 1.0, v2
	v_pk_mul_f32 v[24:25], v[26:27], 0.5 op_sel_hi:[1,0]
	v_pk_add_f32 v[22:23], v[22:23], 1.0 op_sel_hi:[1,0]
	v_rcp_f32_e32 v26, v2
	v_add_f32_e32 v2, 1.0, v21
	v_rcp_f32_e32 v27, v2
	v_pk_mul_f32 v[22:23], v[24:25], v[22:23]
	v_mul_f32_e32 v2, 0x3d372713, v30
	v_cvt_pk_bf16_f32 v21, v22, v23
	v_mul_f32_e32 v2, v30, v2
	v_mul_f32_e32 v22, 0x3d372713, v31
	v_fma_f32 v2, v30, v2, v30
	v_mul_f32_e32 v22, v31, v22
	v_mul_f32_e32 v2, 0x3f4c422a, v2
	v_fma_f32 v22, v31, v22, v31
	v_add_f32_e32 v2, v2, v2
	v_mul_f32_e32 v22, 0x3f4c422a, v22
	v_mul_f32_e32 v2, 0x3fb8aa3b, v2
	v_add_f32_e32 v22, v22, v22
	v_exp_f32_e32 v2, v2
	v_mul_f32_e32 v22, 0x3fb8aa3b, v22
	v_exp_f32_e32 v25, v22
	global_store_dwordx2 v[36:37], v[20:21], off offset:16
	v_pk_fma_f32 v[20:21], v[26:27], 2.0, 1.0 op_sel_hi:[1,0,0] neg_lo:[1,0,0] neg_hi:[1,0,0]
	v_add_f32_e32 v2, 1.0, v2
	v_pk_mul_f32 v[22:23], v[28:29], 0.5 op_sel_hi:[1,0]
	v_rcp_f32_e32 v24, v2
	v_add_f32_e32 v2, 1.0, v25
	v_pk_add_f32 v[20:21], v[20:21], 1.0 op_sel_hi:[1,0]
	v_rcp_f32_e32 v25, v2
	v_pk_mul_f32 v[20:21], v[22:23], v[20:21]
	v_mul_f32_e32 v2, 0x3d372713, v32
	v_cvt_pk_bf16_f32 v20, v20, v21
	v_mul_f32_e32 v2, v32, v2
	v_mul_f32_e32 v21, 0x3d372713, v33
	v_fma_f32 v2, v32, v2, v32
	v_mul_f32_e32 v21, v33, v21
	v_mul_f32_e32 v2, 0x3f4c422a, v2
	v_fma_f32 v21, v33, v21, v33
	v_add_f32_e32 v2, v2, v2
	v_mul_f32_e32 v21, 0x3f4c422a, v21
	v_pk_fma_f32 v[22:23], v[24:25], 2.0, 1.0 op_sel_hi:[1,0,0] neg_lo:[1,0,0] neg_hi:[1,0,0]
	v_mul_f32_e32 v2, 0x3fb8aa3b, v2
	v_add_f32_e32 v21, v21, v21
	v_pk_mul_f32 v[24:25], v[30:31], 0.5 op_sel_hi:[1,0]
	v_pk_add_f32 v[22:23], v[22:23], 1.0 op_sel_hi:[1,0]
	v_exp_f32_e32 v2, v2
	v_mul_f32_e32 v21, 0x3fb8aa3b, v21
	v_pk_mul_f32 v[22:23], v[24:25], v[22:23]
	v_exp_f32_e32 v24, v21
	v_add_f32_e32 v2, 1.0, v2
	v_cvt_pk_bf16_f32 v21, v22, v23
	v_rcp_f32_e32 v22, v2
	v_add_f32_e32 v2, 1.0, v24
	v_rcp_f32_e32 v23, v2
	v_add_co_u32_e32 v24, vcc, s70, v36
	v_mul_f32_e32 v2, 0x3d372713, v34
	s_nop 0
	v_addc_co_u32_e32 v25, vcc, 0, v37, vcc
	global_store_dwordx2 v[24:25], v[20:21], off
	v_pk_fma_f32 v[20:21], v[22:23], 2.0, 1.0 op_sel_hi:[1,0,0] neg_lo:[1,0,0] neg_hi:[1,0,0]
	v_mul_f32_e32 v2, v34, v2
	v_mul_f32_e32 v22, 0x3d372713, v35
	v_fma_f32 v2, v34, v2, v34
	v_mul_f32_e32 v22, v35, v22
	v_mul_f32_e32 v2, 0x3f4c422a, v2
	v_fma_f32 v22, v35, v22, v35
	v_add_f32_e32 v2, v2, v2
	v_mul_f32_e32 v22, 0x3f4c422a, v22
	v_mul_f32_e32 v2, 0x3fb8aa3b, v2
	v_add_f32_e32 v22, v22, v22
	v_exp_f32_e32 v2, v2
	v_mul_f32_e32 v22, 0x3fb8aa3b, v22
	v_exp_f32_e32 v27, v22
	v_pk_mul_f32 v[22:23], v[32:33], 0.5 op_sel_hi:[1,0]
	v_add_f32_e32 v2, 1.0, v2
	v_rcp_f32_e32 v26, v2
	v_add_f32_e32 v2, 1.0, v27
	v_rcp_f32_e32 v27, v2
	v_pk_add_f32 v[20:21], v[20:21], 1.0 op_sel_hi:[1,0]
	s_nop 0
	v_pk_mul_f32 v[20:21], v[22:23], v[20:21]
	v_pk_fma_f32 v[22:23], v[26:27], 2.0, 1.0 op_sel_hi:[1,0,0] neg_lo:[1,0,0] neg_hi:[1,0,0]
	v_pk_mul_f32 v[26:27], v[34:35], 0.5 op_sel_hi:[1,0]
	v_pk_add_f32 v[22:23], v[22:23], 1.0 op_sel_hi:[1,0]
	v_cvt_pk_bf16_f32 v20, v20, v21
	v_pk_mul_f32 v[22:23], v[26:27], v[22:23]
	s_nop 0
	v_cvt_pk_bf16_f32 v21, v22, v23
	global_store_dwordx2 v[24:25], v[20:21], off offset:16
	v_mul_f32_e32 v2, 0x3d372713, v4
	v_mul_f32_e32 v2, v4, v2
	v_mul_f32_e32 v21, 0x3d372713, v5
	v_fma_f32 v2, v4, v2, v4
	v_mul_f32_e32 v21, v5, v21
	v_mul_f32_e32 v2, 0x3f4c422a, v2
	v_fma_f32 v21, v5, v21, v5
	v_add_f32_e32 v2, v2, v2
	v_mul_f32_e32 v21, 0x3f4c422a, v21
	v_mul_f32_e32 v2, 0x3fb8aa3b, v2
	v_add_f32_e32 v21, v21, v21
	v_exp_f32_e32 v2, v2
	v_mul_f32_e32 v21, 0x3fb8aa3b, v21
	v_exp_f32_e32 v21, v21
	v_mul_f32_e32 v24, 0x3d372713, v7
	v_add_f32_e32 v2, 1.0, v2
	v_rcp_f32_e32 v22, v2
	v_add_f32_e32 v2, 1.0, v21
	v_rcp_f32_e32 v23, v2
	v_mul_f32_e32 v2, 0x3d372713, v6
	v_mul_f32_e32 v2, v6, v2
	v_fma_f32 v2, v6, v2, v6
	v_mul_f32_e32 v24, v7, v24
	v_mul_f32_e32 v2, 0x3f4c422a, v2
	v_fma_f32 v24, v7, v24, v7
	v_add_f32_e32 v2, v2, v2
	v_mul_f32_e32 v24, 0x3f4c422a, v24
	v_mul_f32_e32 v2, 0x3fb8aa3b, v2
	v_add_f32_e32 v24, v24, v24
	v_exp_f32_e32 v2, v2
	v_mul_f32_e32 v24, 0x3fb8aa3b, v24
	v_exp_f32_e32 v25, v24
	v_pk_fma_f32 v[22:23], v[22:23], 2.0, 1.0 op_sel_hi:[1,0,0] neg_lo:[1,0,0] neg_hi:[1,0,0]
	v_add_f32_e32 v2, 1.0, v2
	v_pk_mul_f32 v[4:5], v[4:5], 0.5 op_sel_hi:[1,0]
	v_rcp_f32_e32 v24, v2
	v_add_f32_e32 v2, 1.0, v25
	v_pk_add_f32 v[22:23], v[22:23], 1.0 op_sel_hi:[1,0]
	v_rcp_f32_e32 v25, v2
	v_pk_mul_f32 v[4:5], v[4:5], v[22:23]
	v_mul_f32_e32 v2, 0x3d372713, v8
	v_cvt_pk_bf16_f32 v4, v4, v5
	v_mul_f32_e32 v2, v8, v2
	v_mul_f32_e32 v5, 0x3d372713, v9
	v_fma_f32 v2, v8, v2, v8
	v_mul_f32_e32 v5, v9, v5
	v_mul_f32_e32 v2, 0x3f4c422a, v2
	v_fma_f32 v5, v9, v5, v9
	v_add_f32_e32 v2, v2, v2
	v_mul_f32_e32 v5, 0x3f4c422a, v5
	v_mul_f32_e32 v2, 0x3fb8aa3b, v2
	v_add_f32_e32 v5, v5, v5
	v_exp_f32_e32 v2, v2
	v_mul_f32_e32 v5, 0x3fb8aa3b, v5
	v_exp_f32_e32 v5, v5
	v_pk_fma_f32 v[22:23], v[24:25], 2.0, 1.0 op_sel_hi:[1,0,0] neg_lo:[1,0,0] neg_hi:[1,0,0]
	v_add_f32_e32 v2, 1.0, v2
	v_pk_mul_f32 v[6:7], v[6:7], 0.5 op_sel_hi:[1,0]
	v_pk_add_f32 v[22:23], v[22:23], 1.0 op_sel_hi:[1,0]
	v_rcp_f32_e32 v24, v2
	v_add_f32_e32 v2, 1.0, v5
	v_rcp_f32_e32 v25, v2
	v_pk_mul_f32 v[6:7], v[6:7], v[22:23]
	v_mul_f32_e32 v2, 0x3d372713, v10
	v_cvt_pk_bf16_f32 v5, v6, v7
	v_mul_f32_e32 v2, v10, v2
	v_mul_f32_e32 v6, 0x3d372713, v11
	v_fma_f32 v2, v10, v2, v10
	v_mul_f32_e32 v6, v11, v6
	v_mul_f32_e32 v2, 0x3f4c422a, v2
	v_fma_f32 v6, v11, v6, v11
	v_add_f32_e32 v2, v2, v2
	v_mul_f32_e32 v6, 0x3f4c422a, v6
	v_mul_f32_e32 v2, 0x3fb8aa3b, v2
	v_add_f32_e32 v6, v6, v6
	v_mov_b32_e32 v20, v215
	v_exp_f32_e32 v2, v2
	v_mul_f32_e32 v6, 0x3fb8aa3b, v6
	v_exp_f32_e32 v22, v6
	v_ashrrev_i32_e32 v21, 31, v20
	v_lshlrev_b64 v[20:21], 12, v[20:21]
	v_lshl_add_u64 v[20:21], v[196:197], 0, v[20:21]
	global_store_dwordx2 v[20:21], v[4:5], off
	v_pk_fma_f32 v[4:5], v[24:25], 2.0, 1.0 op_sel_hi:[1,0,0] neg_lo:[1,0,0] neg_hi:[1,0,0]
	v_add_f32_e32 v2, 1.0, v2
	v_pk_mul_f32 v[6:7], v[8:9], 0.5 op_sel_hi:[1,0]
	v_rcp_f32_e32 v8, v2
	v_add_f32_e32 v2, 1.0, v22
	v_pk_add_f32 v[4:5], v[4:5], 1.0 op_sel_hi:[1,0]
	v_rcp_f32_e32 v9, v2
	v_pk_mul_f32 v[4:5], v[6:7], v[4:5]
	v_mul_f32_e32 v2, 0x3d372713, v12
	v_cvt_pk_bf16_f32 v4, v4, v5
	v_mul_f32_e32 v2, v12, v2
	v_mul_f32_e32 v5, 0x3d372713, v13
	v_fma_f32 v2, v12, v2, v12
	v_mul_f32_e32 v5, v13, v5
	v_mul_f32_e32 v2, 0x3f4c422a, v2
	v_fma_f32 v5, v13, v5, v13
	v_add_f32_e32 v2, v2, v2
	v_mul_f32_e32 v5, 0x3f4c422a, v5
	v_mul_f32_e32 v2, 0x3fb8aa3b, v2
	v_add_f32_e32 v5, v5, v5
	v_exp_f32_e32 v2, v2
	v_mul_f32_e32 v5, 0x3fb8aa3b, v5
	v_exp_f32_e32 v5, v5
	v_pk_fma_f32 v[6:7], v[8:9], 2.0, 1.0 op_sel_hi:[1,0,0] neg_lo:[1,0,0] neg_hi:[1,0,0]
	v_add_f32_e32 v2, 1.0, v2
	v_pk_mul_f32 v[8:9], v[10:11], 0.5 op_sel_hi:[1,0]
	v_pk_add_f32 v[6:7], v[6:7], 1.0 op_sel_hi:[1,0]
	v_rcp_f32_e32 v10, v2
	v_add_f32_e32 v2, 1.0, v5
	v_rcp_f32_e32 v11, v2
	v_pk_mul_f32 v[6:7], v[8:9], v[6:7]
	v_mul_f32_e32 v2, 0x3d372713, v14
	v_cvt_pk_bf16_f32 v5, v6, v7
	v_mul_f32_e32 v2, v14, v2
	v_mul_f32_e32 v6, 0x3d372713, v15
	v_fma_f32 v2, v14, v2, v14
	v_mul_f32_e32 v6, v15, v6
	v_mul_f32_e32 v2, 0x3f4c422a, v2
	v_fma_f32 v6, v15, v6, v15
	v_add_f32_e32 v2, v2, v2
	v_mul_f32_e32 v6, 0x3f4c422a, v6
	v_mul_f32_e32 v2, 0x3fb8aa3b, v2
	v_add_f32_e32 v6, v6, v6
	v_exp_f32_e32 v2, v2
	v_mul_f32_e32 v6, 0x3fb8aa3b, v6
	v_exp_f32_e32 v9, v6
	global_store_dwordx2 v[20:21], v[4:5], off offset:16
	v_pk_fma_f32 v[4:5], v[10:11], 2.0, 1.0 op_sel_hi:[1,0,0] neg_lo:[1,0,0] neg_hi:[1,0,0]
	v_add_f32_e32 v2, 1.0, v2
	v_pk_mul_f32 v[6:7], v[12:13], 0.5 op_sel_hi:[1,0]
	v_rcp_f32_e32 v8, v2
	v_add_f32_e32 v2, 1.0, v9
	v_pk_add_f32 v[4:5], v[4:5], 1.0 op_sel_hi:[1,0]
	v_rcp_f32_e32 v9, v2
	v_pk_mul_f32 v[4:5], v[6:7], v[4:5]
	v_mul_f32_e32 v2, 0x3d372713, v16
	v_cvt_pk_bf16_f32 v4, v4, v5
	v_mul_f32_e32 v2, v16, v2
	v_mul_f32_e32 v5, 0x3d372713, v17
	v_fma_f32 v2, v16, v2, v16
	v_mul_f32_e32 v5, v17, v5
	v_mul_f32_e32 v2, 0x3f4c422a, v2
	v_fma_f32 v5, v17, v5, v17
	v_add_f32_e32 v2, v2, v2
	v_mul_f32_e32 v5, 0x3f4c422a, v5
	v_pk_fma_f32 v[6:7], v[8:9], 2.0, 1.0 op_sel_hi:[1,0,0] neg_lo:[1,0,0] neg_hi:[1,0,0]
	v_mul_f32_e32 v2, 0x3fb8aa3b, v2
	v_add_f32_e32 v5, v5, v5
	v_pk_mul_f32 v[8:9], v[14:15], 0.5 op_sel_hi:[1,0]
	v_pk_add_f32 v[6:7], v[6:7], 1.0 op_sel_hi:[1,0]
	v_exp_f32_e32 v2, v2
	v_mul_f32_e32 v5, 0x3fb8aa3b, v5
	v_pk_mul_f32 v[6:7], v[8:9], v[6:7]
	v_exp_f32_e32 v8, v5
	v_add_f32_e32 v2, 1.0, v2
	v_cvt_pk_bf16_f32 v5, v6, v7
	v_rcp_f32_e32 v6, v2
	v_add_f32_e32 v2, 1.0, v8
	v_rcp_f32_e32 v7, v2
	v_add_co_u32_e32 v8, vcc, s70, v20
	v_mul_f32_e32 v2, 0x3d372713, v18
	s_nop 0
	v_addc_co_u32_e32 v9, vcc, 0, v21, vcc
	global_store_dwordx2 v[8:9], v[4:5], off
	v_pk_fma_f32 v[4:5], v[6:7], 2.0, 1.0 op_sel_hi:[1,0,0] neg_lo:[1,0,0] neg_hi:[1,0,0]
	v_mul_f32_e32 v2, v18, v2
	v_mul_f32_e32 v6, 0x3d372713, v19
	v_fma_f32 v2, v18, v2, v18
	v_mul_f32_e32 v6, v19, v6
	v_mul_f32_e32 v2, 0x3f4c422a, v2
	v_fma_f32 v6, v19, v6, v19
	v_add_f32_e32 v2, v2, v2
	v_mul_f32_e32 v6, 0x3f4c422a, v6
	v_mul_f32_e32 v2, 0x3fb8aa3b, v2
	v_add_f32_e32 v6, v6, v6
	v_exp_f32_e32 v2, v2
	v_mul_f32_e32 v6, 0x3fb8aa3b, v6
	v_exp_f32_e32 v11, v6
	v_pk_mul_f32 v[6:7], v[16:17], 0.5 op_sel_hi:[1,0]
	v_add_f32_e32 v2, 1.0, v2
	v_rcp_f32_e32 v10, v2
	v_add_f32_e32 v2, 1.0, v11
	v_rcp_f32_e32 v11, v2
	v_pk_add_f32 v[4:5], v[4:5], 1.0 op_sel_hi:[1,0]
	s_nop 0
	v_pk_mul_f32 v[4:5], v[6:7], v[4:5]
	v_pk_fma_f32 v[6:7], v[10:11], 2.0, 1.0 op_sel_hi:[1,0,0] neg_lo:[1,0,0] neg_hi:[1,0,0]
	v_pk_mul_f32 v[10:11], v[18:19], 0.5 op_sel_hi:[1,0]
	v_pk_add_f32 v[6:7], v[6:7], 1.0 op_sel_hi:[1,0]
	v_cvt_pk_bf16_f32 v4, v4, v5
	v_pk_mul_f32 v[6:7], v[10:11], v[6:7]
	s_nop 0
	v_cvt_pk_bf16_f32 v5, v6, v7
	global_store_dwordx2 v[8:9], v[4:5], off offset:16
	v_mov_b32_e32 v16, v3
	v_mov_b32_e32 v17, v3
	v_mov_b32_e32 v2, v3
	v_mov_b32_e32 v4, v3
	v_mov_b32_e32 v5, v3
	v_mov_b32_e32 v6, v3
	v_mov_b32_e32 v7, v3
	v_mov_b32_e32 v8, v3
	v_mov_b32_e32 v9, v3
	v_mov_b32_e32 v10, v3
	v_mov_b32_e32 v11, v3
	v_mov_b32_e32 v12, v3
	v_mov_b32_e32 v13, v3
	v_mov_b32_e32 v14, v3
	v_mov_b32_e32 v15, v3
	v_mov_b32_e32 v18, 0
	v_mov_b64_e32 v[48:49], v[16:17]
	v_mov_b64_e32 v[64:65], v[16:17]
	v_mov_b64_e32 v[80:81], v[16:17]
	v_mov_b64_e32 v[96:97], v[16:17]
	v_mov_b64_e32 v[112:113], v[16:17]
	v_mov_b64_e32 v[128:129], v[16:17]
	v_mov_b64_e32 v[144:145], v[16:17]
	s_mov_b64 s[34:35], 0
	v_mov_b64_e32 v[46:47], v[14:15]
	v_mov_b64_e32 v[44:45], v[12:13]
	v_mov_b64_e32 v[42:43], v[10:11]
	v_mov_b64_e32 v[40:41], v[8:9]
	v_mov_b64_e32 v[38:39], v[6:7]
	v_mov_b64_e32 v[36:37], v[4:5]
	v_mov_b64_e32 v[34:35], v[2:3]
	v_mov_b64_e32 v[62:63], v[14:15]
	v_mov_b64_e32 v[60:61], v[12:13]
	v_mov_b64_e32 v[58:59], v[10:11]
	v_mov_b64_e32 v[56:57], v[8:9]
	v_mov_b64_e32 v[54:55], v[6:7]
	v_mov_b64_e32 v[52:53], v[4:5]
	v_mov_b64_e32 v[50:51], v[2:3]
	v_mov_b64_e32 v[78:79], v[14:15]
	v_mov_b64_e32 v[76:77], v[12:13]
	v_mov_b64_e32 v[74:75], v[10:11]
	v_mov_b64_e32 v[72:73], v[8:9]
	v_mov_b64_e32 v[70:71], v[6:7]
	v_mov_b64_e32 v[68:69], v[4:5]
	v_mov_b64_e32 v[66:67], v[2:3]
	v_mov_b64_e32 v[94:95], v[14:15]
	v_mov_b64_e32 v[92:93], v[12:13]
	v_mov_b64_e32 v[90:91], v[10:11]
	v_mov_b64_e32 v[88:89], v[8:9]
	v_mov_b64_e32 v[86:87], v[6:7]
	v_mov_b64_e32 v[84:85], v[4:5]
	v_mov_b64_e32 v[82:83], v[2:3]
	v_mov_b64_e32 v[110:111], v[14:15]
	v_mov_b64_e32 v[108:109], v[12:13]
	v_mov_b64_e32 v[106:107], v[10:11]
	v_mov_b64_e32 v[104:105], v[8:9]
	v_mov_b64_e32 v[102:103], v[6:7]
	v_mov_b64_e32 v[100:101], v[4:5]
	v_mov_b64_e32 v[98:99], v[2:3]
	v_mov_b64_e32 v[126:127], v[14:15]
	v_mov_b64_e32 v[124:125], v[12:13]
	v_mov_b64_e32 v[122:123], v[10:11]
	v_mov_b64_e32 v[120:121], v[8:9]
	v_mov_b64_e32 v[118:119], v[6:7]
	v_mov_b64_e32 v[116:117], v[4:5]
	v_mov_b64_e32 v[114:115], v[2:3]
	v_mov_b64_e32 v[142:143], v[14:15]
	v_mov_b64_e32 v[140:141], v[12:13]
	v_mov_b64_e32 v[138:139], v[10:11]
	v_mov_b64_e32 v[136:137], v[8:9]
	v_mov_b64_e32 v[134:135], v[6:7]
	v_mov_b64_e32 v[132:133], v[4:5]
	v_mov_b64_e32 v[130:131], v[2:3]
	v_mov_b32_e32 v19, v18
	v_mov_b32_e32 v20, v18
	v_mov_b32_e32 v21, v18
	v_mov_b32_e32 v22, v18
	v_mov_b32_e32 v23, v18
	v_mov_b32_e32 v24, v18
	v_mov_b32_e32 v25, v18
	v_mov_b32_e32 v26, v18
	v_mov_b32_e32 v27, v18
	v_mov_b32_e32 v28, v18
	v_mov_b32_e32 v29, v18
	v_mov_b32_e32 v30, v18
	v_mov_b32_e32 v31, v18
	v_mov_b32_e32 v32, v18
	v_mov_b32_e32 v33, v18
	s_branch .LBB0_816
